# GEMM epilogue dwordx4 stores marked non-temporal (nt)
# baseline (speedup 1.0000x reference)
.LBB0_165:
	v_lshl_or_b32 v174, s64, 8, v190
	v_lshl_add_u32 v186, s62, 8, v188
	v_ashrrev_i32_e32 v175, 31, v174
	v_readlane_b32 s0, v254, 43
	v_lshlrev_b64 v[200:201], 1, v[174:175]
	v_readlane_b32 s1, v254, 44
	v_ashrrev_i32_e32 v187, 31, v186
	v_lshlrev_b64 v[178:179], 11, v[186:187]
	v_lshl_add_u64 v[176:177], s[0:1], 0, v[200:201]
	v_lshl_add_u64 v[114:115], v[176:177], 0, v[178:179]
	global_load_dwordx4 v[192:195], v[114:115], off
	global_load_dwordx4 v[196:199], v[114:115], off offset:256
	v_or_b32_e32 v114, 16, v186
	v_ashrrev_i32_e32 v115, 31, v114
	v_lshlrev_b64 v[184:185], 11, v[114:115]
	v_lshl_add_u64 v[114:115], v[176:177], 0, v[184:185]
	global_load_dwordx4 v[134:137], v[114:115], off
	global_load_dwordx4 v[130:133], v[114:115], off offset:256
	v_or_b32_e32 v114, 32, v186
	v_ashrrev_i32_e32 v115, 31, v114
	v_lshlrev_b64 v[182:183], 11, v[114:115]
	v_lshl_add_u64 v[114:115], v[176:177], 0, v[182:183]
	global_load_dwordx4 v[126:129], v[114:115], off
	global_load_dwordx4 v[122:125], v[114:115], off offset:256
	v_or_b32_e32 v114, 48, v186
	v_ashrrev_i32_e32 v115, 31, v114
	v_lshlrev_b64 v[180:181], 11, v[114:115]
	v_lshl_add_u64 v[114:115], v[176:177], 0, v[180:181]
	global_load_dwordx4 v[118:121], v[114:115], off
	s_nop 0
	global_load_dwordx4 v[114:117], v[114:115], off offset:256
	s_waitcnt vmcnt(0)
	v_lshlrev_b32_e32 v202, 16, v192
	v_add_f32_e32 v202, v150, v202
	v_and_b32_e32 v150, 0xffff0000, v192
	v_add_f32_e32 v192, v151, v150
	v_lshlrev_b32_e32 v150, 16, v193
	v_add_f32_e32 v152, v152, v150
	v_and_b32_e32 v150, 0xffff0000, v193
	v_add_f32_e32 v153, v153, v150
	v_lshlrev_b32_e32 v150, 16, v194
	v_add_f32_e32 v193, v146, v150
	v_and_b32_e32 v146, 0xffff0000, v194
	v_add_f32_e32 v194, v147, v146
	v_lshlrev_b32_e32 v146, 16, v195
	v_add_f32_e32 v203, v148, v146
	v_and_b32_e32 v146, 0xffff0000, v195
	v_lshl_add_u64 v[150:151], s[0:1], 0, v[178:179]
	v_add_f32_e32 v195, v149, v146
	v_cvt_pk_bf16_f32 v146, v202, v192
	v_cvt_pk_bf16_f32 v147, v152, v153
	v_lshl_add_u64 v[150:151], v[150:151], 0, v[200:201]
	v_cvt_pk_bf16_f32 v148, v193, v194
	v_cvt_pk_bf16_f32 v149, v203, v195
	global_store_dwordx4 v[150:151], v[146:149], off nt
	s_nop 1
	v_mul_f32_e32 v146, v192, v192
	v_mul_f32_e32 v147, v153, v153
	v_fmac_f32_e32 v146, v202, v202
	v_fmac_f32_e32 v147, v152, v152
	v_add_f32_e32 v146, v146, v147
	v_mul_f32_e32 v147, v194, v194
	v_fmac_f32_e32 v147, v193, v193
	v_add_f32_e32 v146, v147, v146
	v_mul_f32_e32 v147, v195, v195
	v_fmac_f32_e32 v147, v203, v203
	v_add_f32_e32 v146, v147, v146
	v_lshlrev_b32_e32 v147, 16, v196
	v_add_f32_e32 v142, v142, v147
	v_and_b32_e32 v147, 0xffff0000, v196
	v_add_f32_e32 v143, v143, v147
	v_lshlrev_b32_e32 v147, 16, v197
	v_add_f32_e32 v144, v144, v147
	v_and_b32_e32 v147, 0xffff0000, v197
	v_add_f32_e32 v145, v145, v147
	v_lshlrev_b32_e32 v147, 16, v198
	v_add_f32_e32 v147, v138, v147
	v_and_b32_e32 v138, 0xffff0000, v198
	v_add_f32_e32 v148, v139, v138
	v_lshlrev_b32_e32 v138, 16, v199
	v_add_f32_e32 v149, v140, v138
	v_and_b32_e32 v138, 0xffff0000, v199
	v_add_f32_e32 v152, v141, v138
	v_cvt_pk_bf16_f32 v138, v142, v143
	v_cvt_pk_bf16_f32 v139, v144, v145
	v_cvt_pk_bf16_f32 v140, v147, v148
	v_cvt_pk_bf16_f32 v141, v149, v152
	global_store_dwordx4 v[150:151], v[138:141], off offset:256 nt
	s_nop 1
	v_mul_f32_e32 v138, v143, v143
	v_mul_f32_e32 v139, v145, v145
	v_fmac_f32_e32 v138, v142, v142
	v_fmac_f32_e32 v139, v144, v144
	v_add_f32_e32 v138, v138, v139
	v_mul_f32_e32 v139, v148, v148
	v_fmac_f32_e32 v139, v147, v147
	v_add_f32_e32 v138, v139, v138
	v_mul_f32_e32 v139, v152, v152
	v_fmac_f32_e32 v139, v149, v149
	v_and_b32_e32 v140, 64, v211
	v_add_f32_e32 v138, v139, v138
	v_xor_b32_e32 v139, 16, v211
	v_add_u32_e32 v141, 64, v140
	v_cmp_lt_i32_e32 vcc, v139, v141
	v_add_f32_e32 v138, v146, v138
	s_nop 0
	v_cndmask_b32_e32 v139, v211, v139, vcc
	v_lshlrev_b32_e32 v140, 2, v139
	ds_bpermute_b32 v139, v140, v138
	s_waitcnt lgkmcnt(0)
	v_add_f32_e32 v142, v138, v139
	v_xor_b32_e32 v138, 32, v211
	v_cmp_lt_i32_e32 vcc, v138, v141
	s_nop 1
	v_cndmask_b32_e32 v138, v211, v138, vcc
	v_lshlrev_b32_e32 v141, 2, v138
	ds_bpermute_b32 v143, v141, v142
	v_lshl_add_u64 v[138:139], v[186:187], 3, s[36:37]
	s_and_saveexec_b64 s[0:1], s[40:41]
	v_readlane_b32 s66, v254, 47
	v_readlane_b32 s67, v254, 48
	s_load_dwordx2 s[78:79], s[66:67], 0x98
	s_movk_i32 s22, 0x5800
	s_mov_b32 s23, 0xb000
	s_mov_b32 s24, 0x3f317217
	s_cbranch_execz .LBB0_167
	s_waitcnt lgkmcnt(0)
	v_add_f32_e32 v142, v142, v143
	v_mul_f32_e32 v142, 0x4b800000, v142
	v_rndne_f32_e32 v142, v142
	v_mul_f32_e32 v143, 0x2f800000, v142
	v_floor_f32_e32 v143, v143
	v_fmac_f32_e32 v142, 0xcf800000, v143
	v_cvt_u32_f32_e32 v142, v142
	v_cvt_u32_f32_e32 v143, v143
	global_atomic_add_x2 v[138:139], v[142:143], off
.LBB0_167:
	s_or_b64 exec, exec, s[0:1]
	v_lshlrev_b32_e32 v142, 16, v134
	v_and_b32_e32 v134, 0xffff0000, v134
	v_add_f32_e32 v111, v111, v134
	v_lshlrev_b32_e32 v134, 16, v135
	v_add_f32_e32 v112, v112, v134
	v_and_b32_e32 v134, 0xffff0000, v135
	v_add_f32_e32 v113, v113, v134
	v_lshlrev_b32_e32 v134, 16, v136
	v_add_f32_e32 v134, v106, v134
	v_and_b32_e32 v106, 0xffff0000, v136
	v_add_f32_e32 v135, v107, v106
	v_lshlrev_b32_e32 v106, 16, v137
	v_add_f32_e32 v136, v108, v106
	v_and_b32_e32 v106, 0xffff0000, v137
	v_add_f32_e32 v110, v110, v142
	v_add_f32_e32 v137, v109, v106
	v_cvt_pk_bf16_f32 v106, v110, v111
	v_mul_f32_e32 v111, v111, v111
	v_fmac_f32_e32 v111, v110, v110
	v_mul_f32_e32 v110, v113, v113
	v_fmac_f32_e32 v110, v112, v112
	v_add_f32_e32 v110, v111, v110
	v_mul_f32_e32 v111, v135, v135
	v_fmac_f32_e32 v111, v134, v134
	v_add_f32_e32 v110, v111, v110
	v_mul_f32_e32 v111, v137, v137
	v_fmac_f32_e32 v111, v136, v136
	v_add_f32_e32 v110, v111, v110
	v_lshlrev_b32_e32 v111, 16, v130
	v_add_f32_e32 v102, v102, v111
	v_and_b32_e32 v111, 0xffff0000, v130
	v_add_f32_e32 v103, v103, v111
	v_lshlrev_b32_e32 v111, 16, v131
	v_add_f32_e32 v111, v104, v111
	v_and_b32_e32 v104, 0xffff0000, v131
	v_cvt_pk_bf16_f32 v107, v112, v113
	v_add_f32_e32 v112, v105, v104
	v_lshlrev_b32_e32 v104, 16, v132
	v_add_f32_e32 v113, v98, v104
	v_and_b32_e32 v98, 0xffff0000, v132
	v_add_f32_e32 v130, v99, v98
	v_lshlrev_b32_e32 v98, 16, v133
	v_add_f32_e32 v131, v100, v98
	v_and_b32_e32 v98, 0xffff0000, v133
	v_add_f32_e32 v132, v101, v98
	v_mul_f32_e32 v98, v103, v103
	v_mul_f32_e32 v99, v112, v112
	v_fmac_f32_e32 v98, v102, v102
	v_fmac_f32_e32 v99, v111, v111
	v_add_f32_e32 v98, v98, v99
	v_mul_f32_e32 v99, v130, v130
	v_fmac_f32_e32 v99, v113, v113
	v_add_f32_e32 v98, v99, v98
	v_mul_f32_e32 v99, v132, v132
	v_fmac_f32_e32 v99, v131, v131
	v_add_f32_e32 v98, v99, v98
	v_add_f32_e32 v101, v110, v98
	ds_bpermute_b32 v110, v140, v101
	v_readlane_b32 s0, v254, 43
	v_readlane_b32 s1, v254, 44
	v_cvt_pk_bf16_f32 v108, v134, v135
	v_cvt_pk_bf16_f32 v109, v136, v137
	v_cvt_pk_bf16_f32 v100, v102, v103
	v_cvt_pk_bf16_f32 v102, v113, v130
	v_cvt_pk_bf16_f32 v103, v131, v132
	s_nop 1
	v_lshl_add_u64 v[98:99], s[0:1], 0, v[184:185]
	v_lshl_add_u64 v[104:105], v[174:175], 1, v[98:99]
	s_waitcnt lgkmcnt(0)
	v_add_f32_e32 v98, v101, v110
	ds_bpermute_b32 v99, v141, v98
	global_store_dwordx4 v[104:105], v[106:109], off nt
	v_cvt_pk_bf16_f32 v101, v111, v112
	global_store_dwordx4 v[104:105], v[100:103], off offset:256 nt
	s_and_saveexec_b64 s[0:1], s[40:41]
	s_cbranch_execz .LBB0_169
	s_waitcnt lgkmcnt(0)
	v_add_f32_e32 v98, v98, v99
	v_mul_f32_e32 v98, 0x4b800000, v98
	v_rndne_f32_e32 v98, v98
	v_mul_f32_e32 v99, 0x2f800000, v98
	v_floor_f32_e32 v99, v99
	v_fmac_f32_e32 v98, 0xcf800000, v99
	v_cvt_u32_f32_e32 v98, v98
	v_cvt_u32_f32_e32 v99, v99
	global_atomic_add_x2 v[138:139], v[98:99], off offset:128
.LBB0_169:
	s_or_b64 exec, exec, s[0:1]
	v_lshlrev_b32_e32 v98, 16, v126
	v_add_f32_e32 v94, v94, v98
	v_and_b32_e32 v98, 0xffff0000, v126
	v_add_f32_e32 v95, v95, v98
	v_lshlrev_b32_e32 v98, 16, v127
	v_add_f32_e32 v96, v96, v98
	v_and_b32_e32 v98, 0xffff0000, v127
	v_add_f32_e32 v97, v97, v98
	v_lshlrev_b32_e32 v98, 16, v128
	v_add_f32_e32 v98, v90, v98
	v_and_b32_e32 v90, 0xffff0000, v128
	s_waitcnt lgkmcnt(0)
	v_add_f32_e32 v99, v91, v90
	v_lshlrev_b32_e32 v90, 16, v129
	v_add_f32_e32 v100, v92, v90
	v_and_b32_e32 v90, 0xffff0000, v129
	v_add_f32_e32 v101, v93, v90
	v_cvt_pk_bf16_f32 v90, v94, v95
	v_mul_f32_e32 v95, v95, v95
	v_fmac_f32_e32 v95, v94, v94
	v_mul_f32_e32 v94, v97, v97
	v_fmac_f32_e32 v94, v96, v96
	v_add_f32_e32 v94, v95, v94
	v_mul_f32_e32 v95, v99, v99
	v_fmac_f32_e32 v95, v98, v98
	v_add_f32_e32 v94, v95, v94
	v_mul_f32_e32 v95, v101, v101
	v_fmac_f32_e32 v95, v100, v100
	v_add_f32_e32 v94, v95, v94
	v_lshlrev_b32_e32 v95, 16, v122
	v_add_f32_e32 v86, v86, v95
	v_and_b32_e32 v95, 0xffff0000, v122
	v_add_f32_e32 v87, v87, v95
	v_lshlrev_b32_e32 v95, 16, v123
	v_add_f32_e32 v95, v88, v95
	v_and_b32_e32 v88, 0xffff0000, v123
	v_cvt_pk_bf16_f32 v91, v96, v97
	v_add_f32_e32 v96, v89, v88
	v_lshlrev_b32_e32 v88, 16, v124
	v_add_f32_e32 v97, v82, v88
	v_and_b32_e32 v82, 0xffff0000, v124
	v_cvt_pk_bf16_f32 v92, v98, v99
	v_add_f32_e32 v98, v83, v82
	v_lshlrev_b32_e32 v82, 16, v125
	v_add_f32_e32 v99, v84, v82
	v_and_b32_e32 v82, 0xffff0000, v125
	v_cvt_pk_bf16_f32 v93, v100, v101
	v_add_f32_e32 v100, v85, v82
	v_mul_f32_e32 v82, v87, v87
	v_mul_f32_e32 v83, v96, v96
	v_fmac_f32_e32 v82, v86, v86
	v_fmac_f32_e32 v83, v95, v95
	v_add_f32_e32 v82, v82, v83
	v_mul_f32_e32 v83, v98, v98
	v_fmac_f32_e32 v83, v97, v97
	v_add_f32_e32 v82, v83, v82
	v_mul_f32_e32 v83, v100, v100
	v_fmac_f32_e32 v83, v99, v99
	v_add_f32_e32 v82, v83, v82
	v_add_f32_e32 v85, v94, v82
	ds_bpermute_b32 v94, v140, v85
	v_readlane_b32 s0, v254, 43
	v_readlane_b32 s1, v254, 44
	v_cvt_pk_bf16_f32 v84, v86, v87
	v_cvt_pk_bf16_f32 v86, v97, v98
	v_cvt_pk_bf16_f32 v87, v99, v100
	s_nop 1
	v_lshl_add_u64 v[82:83], s[0:1], 0, v[182:183]
	v_lshl_add_u64 v[88:89], v[174:175], 1, v[82:83]
	s_waitcnt lgkmcnt(0)
	v_add_f32_e32 v82, v85, v94
	ds_bpermute_b32 v83, v141, v82
	global_store_dwordx4 v[88:89], v[90:93], off nt
	v_cvt_pk_bf16_f32 v85, v95, v96
	global_store_dwordx4 v[88:89], v[84:87], off offset:256 nt
	s_and_saveexec_b64 s[0:1], s[40:41]
	v_readlane_b32 s34, v254, 40
	s_cbranch_execz .LBB0_171
	s_waitcnt lgkmcnt(0)
	v_add_f32_e32 v82, v82, v83
	v_mul_f32_e32 v82, 0x4b800000, v82
	v_rndne_f32_e32 v82, v82
	v_mul_f32_e32 v83, 0x2f800000, v82
	v_floor_f32_e32 v83, v83
	v_fmac_f32_e32 v82, 0xcf800000, v83
	v_cvt_u32_f32_e32 v82, v82
	v_cvt_u32_f32_e32 v83, v83
	global_atomic_add_x2 v[138:139], v[82:83], off offset:256
.LBB0_171:
	s_or_b64 exec, exec, s[0:1]
	v_lshlrev_b32_e32 v82, 16, v118
	v_add_f32_e32 v78, v78, v82
	v_and_b32_e32 v82, 0xffff0000, v118
	v_add_f32_e32 v79, v79, v82
	v_lshlrev_b32_e32 v82, 16, v119
	v_add_f32_e32 v80, v80, v82
	v_and_b32_e32 v82, 0xffff0000, v119
	v_add_f32_e32 v81, v81, v82
	v_lshlrev_b32_e32 v82, 16, v120
	v_add_f32_e32 v82, v74, v82
	v_and_b32_e32 v74, 0xffff0000, v120
	s_waitcnt lgkmcnt(0)
	v_add_f32_e32 v83, v75, v74
	v_lshlrev_b32_e32 v74, 16, v121
	v_add_f32_e32 v84, v76, v74
	v_and_b32_e32 v74, 0xffff0000, v121
	v_add_f32_e32 v85, v77, v74
	v_cvt_pk_bf16_f32 v74, v78, v79
	v_mul_f32_e32 v79, v79, v79
	v_fmac_f32_e32 v79, v78, v78
	v_mul_f32_e32 v78, v81, v81
	v_fmac_f32_e32 v78, v80, v80
	v_add_f32_e32 v78, v79, v78
	v_mul_f32_e32 v79, v83, v83
	v_fmac_f32_e32 v79, v82, v82
	v_add_f32_e32 v78, v79, v78
	v_mul_f32_e32 v79, v85, v85
	v_fmac_f32_e32 v79, v84, v84
	v_add_f32_e32 v78, v79, v78
	v_lshlrev_b32_e32 v79, 16, v114
	v_add_f32_e32 v70, v70, v79
	v_and_b32_e32 v79, 0xffff0000, v114
	v_add_f32_e32 v71, v71, v79
	v_lshlrev_b32_e32 v79, 16, v115
	v_add_f32_e32 v79, v72, v79
	v_and_b32_e32 v72, 0xffff0000, v115
	v_cvt_pk_bf16_f32 v75, v80, v81
	v_add_f32_e32 v80, v73, v72
	v_lshlrev_b32_e32 v72, 16, v116
	v_add_f32_e32 v81, v66, v72
	v_and_b32_e32 v66, 0xffff0000, v116
	v_cvt_pk_bf16_f32 v76, v82, v83
	v_add_f32_e32 v82, v67, v66
	v_lshlrev_b32_e32 v66, 16, v117
	v_add_f32_e32 v83, v68, v66
	v_and_b32_e32 v66, 0xffff0000, v117
	v_cvt_pk_bf16_f32 v77, v84, v85
	v_add_f32_e32 v84, v69, v66
	v_mul_f32_e32 v66, v71, v71
	v_mul_f32_e32 v67, v80, v80
	v_fmac_f32_e32 v66, v70, v70
	v_fmac_f32_e32 v67, v79, v79
	v_add_f32_e32 v66, v66, v67
	v_mul_f32_e32 v67, v82, v82
	v_fmac_f32_e32 v67, v81, v81
	v_add_f32_e32 v66, v67, v66
	v_mul_f32_e32 v67, v84, v84
	v_fmac_f32_e32 v67, v83, v83
	v_add_f32_e32 v66, v67, v66
	v_add_f32_e32 v69, v78, v66
	ds_bpermute_b32 v78, v140, v69
	v_readlane_b32 s0, v254, 43
	v_readlane_b32 s1, v254, 44
	v_cvt_pk_bf16_f32 v68, v70, v71
	v_cvt_pk_bf16_f32 v70, v81, v82
	v_cvt_pk_bf16_f32 v71, v83, v84
	s_nop 1
	v_lshl_add_u64 v[66:67], s[0:1], 0, v[180:181]
	v_lshl_add_u64 v[72:73], v[174:175], 1, v[66:67]
	s_waitcnt lgkmcnt(0)
	v_add_f32_e32 v66, v69, v78
	ds_bpermute_b32 v67, v141, v66
	global_store_dwordx4 v[72:73], v[74:77], off nt
	v_cvt_pk_bf16_f32 v69, v79, v80
	global_store_dwordx4 v[72:73], v[68:71], off offset:256 nt
	s_and_saveexec_b64 s[0:1], s[40:41]
	s_cbranch_execz .LBB0_173
	s_waitcnt lgkmcnt(0)
	v_add_f32_e32 v66, v66, v67
	v_mul_f32_e32 v66, 0x4b800000, v66
	v_rndne_f32_e32 v66, v66
	v_mul_f32_e32 v67, 0x2f800000, v66
	v_floor_f32_e32 v67, v67
	v_fmac_f32_e32 v66, 0xcf800000, v67
	v_cvt_u32_f32_e32 v66, v66
	v_cvt_u32_f32_e32 v67, v67
	global_atomic_add_x2 v[138:139], v[66:67], off offset:384
.LBB0_173:
	s_or_b64 exec, exec, s[0:1]
	s_mov_b64 s[0:1], 0x40000
	v_lshl_add_u64 v[104:105], v[178:179], 0, s[0:1]
	s_waitcnt lgkmcnt(0)
	v_lshl_add_u64 v[66:67], v[176:177], 0, v[104:105]
	global_load_dwordx4 v[100:103], v[66:67], off
	global_load_dwordx4 v[90:93], v[66:67], off offset:256
	s_mov_b64 s[0:1], 0x48000
	v_lshl_add_u64 v[98:99], v[178:179], 0, s[0:1]
	s_mov_b64 s[0:1], 0x50000
	v_lshl_add_u64 v[66:67], v[176:177], 0, v[98:99]
	v_lshl_add_u64 v[96:97], v[178:179], 0, s[0:1]
	s_mov_b64 s[0:1], 0x58000
	global_load_dwordx4 v[86:89], v[66:67], off
	global_load_dwordx4 v[82:85], v[66:67], off offset:256
	v_lshl_add_u64 v[66:67], v[176:177], 0, v[96:97]
	v_lshl_add_u64 v[94:95], v[178:179], 0, s[0:1]
	global_load_dwordx4 v[78:81], v[66:67], off
	global_load_dwordx4 v[74:77], v[66:67], off offset:256
	v_lshl_add_u64 v[66:67], v[176:177], 0, v[94:95]
	global_load_dwordx4 v[70:73], v[66:67], off
	s_nop 0
	global_load_dwordx4 v[66:69], v[66:67], off offset:256
	v_readlane_b32 s0, v254, 43
	v_readlane_b32 s1, v254, 44
	s_waitcnt vmcnt(7)
	v_lshlrev_b32_e32 v106, 16, v100
	v_add_f32_e32 v106, v62, v106
	v_and_b32_e32 v62, 0xffff0000, v100
	v_add_f32_e32 v100, v63, v62
	v_lshlrev_b32_e32 v62, 16, v101
	v_add_f32_e32 v64, v64, v62
	v_and_b32_e32 v62, 0xffff0000, v101
	v_add_f32_e32 v65, v65, v62
	v_lshlrev_b32_e32 v62, 16, v102
	v_add_f32_e32 v101, v58, v62
	v_and_b32_e32 v58, 0xffff0000, v102
	v_add_f32_e32 v102, v59, v58
	v_lshlrev_b32_e32 v58, 16, v103
	v_add_f32_e32 v107, v60, v58
	v_and_b32_e32 v58, 0xffff0000, v103
	v_lshl_add_u64 v[62:63], s[0:1], 0, v[104:105]
	v_add_f32_e32 v103, v61, v58
	v_cvt_pk_bf16_f32 v58, v106, v100
	v_cvt_pk_bf16_f32 v59, v64, v65
	v_lshl_add_u64 v[62:63], v[174:175], 1, v[62:63]
	v_cvt_pk_bf16_f32 v60, v101, v102
	v_cvt_pk_bf16_f32 v61, v107, v103
	global_store_dwordx4 v[62:63], v[58:61], off nt
	s_nop 1
	v_mul_f32_e32 v58, v100, v100
	v_mul_f32_e32 v59, v65, v65
	v_fmac_f32_e32 v58, v106, v106
	v_fmac_f32_e32 v59, v64, v64
	v_add_f32_e32 v58, v58, v59
	v_mul_f32_e32 v59, v102, v102
	v_fmac_f32_e32 v59, v101, v101
	v_add_f32_e32 v58, v59, v58
	v_mul_f32_e32 v59, v103, v103
	v_fmac_f32_e32 v59, v107, v107
	v_add_f32_e32 v58, v59, v58
	s_waitcnt vmcnt(7)
	v_lshlrev_b32_e32 v59, 16, v90
	v_add_f32_e32 v54, v54, v59
	v_and_b32_e32 v59, 0xffff0000, v90
	v_add_f32_e32 v55, v55, v59
	v_lshlrev_b32_e32 v59, 16, v91
	v_add_f32_e32 v56, v56, v59
	v_and_b32_e32 v59, 0xffff0000, v91
	v_add_f32_e32 v57, v57, v59
	v_lshlrev_b32_e32 v59, 16, v92
	v_add_f32_e32 v59, v50, v59
	v_and_b32_e32 v50, 0xffff0000, v92
	v_add_f32_e32 v60, v51, v50
	v_lshlrev_b32_e32 v50, 16, v93
	v_add_f32_e32 v61, v52, v50
	v_and_b32_e32 v50, 0xffff0000, v93
	v_add_f32_e32 v64, v53, v50
	v_cvt_pk_bf16_f32 v50, v54, v55
	v_cvt_pk_bf16_f32 v51, v56, v57
	v_cvt_pk_bf16_f32 v52, v59, v60
	v_cvt_pk_bf16_f32 v53, v61, v64
	global_store_dwordx4 v[62:63], v[50:53], off offset:256 nt
	s_nop 1
	v_mul_f32_e32 v50, v55, v55
	v_mul_f32_e32 v51, v57, v57
	v_fmac_f32_e32 v50, v54, v54
	v_fmac_f32_e32 v51, v56, v56
	v_add_f32_e32 v50, v50, v51
	v_mul_f32_e32 v51, v60, v60
	v_fmac_f32_e32 v51, v59, v59
	v_add_f32_e32 v50, v51, v50
	v_mul_f32_e32 v51, v64, v64
	v_fmac_f32_e32 v51, v61, v61
	v_add_f32_e32 v50, v51, v50
	v_add_f32_e32 v50, v58, v50
	ds_bpermute_b32 v51, v140, v50
	s_waitcnt lgkmcnt(0)
	v_add_f32_e32 v50, v50, v51
	ds_bpermute_b32 v51, v141, v50
	s_and_saveexec_b64 s[0:1], s[40:41]
	s_cbranch_execz .LBB0_175
	s_waitcnt lgkmcnt(0)
	v_add_f32_e32 v50, v50, v51
	v_mul_f32_e32 v50, 0x4b800000, v50
	v_rndne_f32_e32 v50, v50
	v_mul_f32_e32 v51, 0x2f800000, v50
	v_floor_f32_e32 v51, v51
	v_fmac_f32_e32 v50, 0xcf800000, v51
	v_cvt_u32_f32_e32 v50, v50
	v_cvt_u32_f32_e32 v51, v51
	global_atomic_add_x2 v[138:139], v[50:51], off offset:1024
.LBB0_175:
	s_or_b64 exec, exec, s[0:1]
	s_waitcnt vmcnt(7)
	v_lshlrev_b32_e32 v50, 16, v86
	v_add_f32_e32 v46, v46, v50
	v_and_b32_e32 v50, 0xffff0000, v86
	v_add_f32_e32 v47, v47, v50
	v_lshlrev_b32_e32 v50, 16, v87
	v_add_f32_e32 v48, v48, v50
	v_and_b32_e32 v50, 0xffff0000, v87
	v_add_f32_e32 v49, v49, v50
	v_lshlrev_b32_e32 v50, 16, v88
	v_add_f32_e32 v50, v42, v50
	v_and_b32_e32 v42, 0xffff0000, v88
	s_waitcnt lgkmcnt(0)
	v_add_f32_e32 v51, v43, v42
	v_lshlrev_b32_e32 v42, 16, v89
	v_add_f32_e32 v52, v44, v42
	v_and_b32_e32 v42, 0xffff0000, v89
	v_add_f32_e32 v53, v45, v42
	v_cvt_pk_bf16_f32 v42, v46, v47
	v_mul_f32_e32 v47, v47, v47
	v_fmac_f32_e32 v47, v46, v46
	v_mul_f32_e32 v46, v49, v49
	v_fmac_f32_e32 v46, v48, v48
	v_add_f32_e32 v46, v47, v46
	v_mul_f32_e32 v47, v51, v51
	v_fmac_f32_e32 v47, v50, v50
	v_add_f32_e32 v46, v47, v46
	v_mul_f32_e32 v47, v53, v53
	v_fmac_f32_e32 v47, v52, v52
	v_add_f32_e32 v46, v47, v46
	s_waitcnt vmcnt(6)
	v_lshlrev_b32_e32 v47, 16, v82
	v_add_f32_e32 v38, v38, v47
	v_and_b32_e32 v47, 0xffff0000, v82
	v_add_f32_e32 v39, v39, v47
	v_lshlrev_b32_e32 v47, 16, v83
	v_add_f32_e32 v47, v40, v47
	v_and_b32_e32 v40, 0xffff0000, v83
	v_cvt_pk_bf16_f32 v43, v48, v49
	v_add_f32_e32 v48, v41, v40
	v_lshlrev_b32_e32 v40, 16, v84
	v_add_f32_e32 v49, v34, v40
	v_and_b32_e32 v34, 0xffff0000, v84
	v_cvt_pk_bf16_f32 v44, v50, v51
	v_add_f32_e32 v50, v35, v34
	v_lshlrev_b32_e32 v34, 16, v85
	v_add_f32_e32 v51, v36, v34
	v_and_b32_e32 v34, 0xffff0000, v85
	v_cvt_pk_bf16_f32 v45, v52, v53
	v_add_f32_e32 v52, v37, v34
	v_mul_f32_e32 v34, v39, v39
	v_mul_f32_e32 v35, v48, v48
	v_fmac_f32_e32 v34, v38, v38
	v_fmac_f32_e32 v35, v47, v47
	v_add_f32_e32 v34, v34, v35
	v_mul_f32_e32 v35, v50, v50
	v_fmac_f32_e32 v35, v49, v49
	v_add_f32_e32 v34, v35, v34
	v_mul_f32_e32 v35, v52, v52
	v_fmac_f32_e32 v35, v51, v51
	v_add_f32_e32 v34, v35, v34
	v_add_f32_e32 v37, v46, v34
	ds_bpermute_b32 v46, v140, v37
	v_readlane_b32 s0, v254, 43
	v_readlane_b32 s1, v254, 44
	v_cvt_pk_bf16_f32 v36, v38, v39
	v_cvt_pk_bf16_f32 v38, v49, v50
	v_cvt_pk_bf16_f32 v39, v51, v52
	s_nop 1
	v_lshl_add_u64 v[34:35], s[0:1], 0, v[98:99]
	v_lshl_add_u64 v[40:41], v[174:175], 1, v[34:35]
	s_waitcnt lgkmcnt(0)
	v_add_f32_e32 v34, v37, v46
	ds_bpermute_b32 v35, v141, v34
	global_store_dwordx4 v[40:41], v[42:45], off nt
	v_cvt_pk_bf16_f32 v37, v47, v48
	global_store_dwordx4 v[40:41], v[36:39], off offset:256 nt
	s_and_saveexec_b64 s[0:1], s[40:41]
	s_cbranch_execz .LBB0_177
	s_waitcnt lgkmcnt(0)
	v_add_f32_e32 v34, v34, v35
	v_mul_f32_e32 v34, 0x4b800000, v34
	v_rndne_f32_e32 v34, v34
	v_mul_f32_e32 v35, 0x2f800000, v34
	v_floor_f32_e32 v35, v35
	v_fmac_f32_e32 v34, 0xcf800000, v35
	v_cvt_u32_f32_e32 v34, v34
	v_cvt_u32_f32_e32 v35, v35
	global_atomic_add_x2 v[138:139], v[34:35], off offset:1152
.LBB0_177:
	s_or_b64 exec, exec, s[0:1]
	s_waitcnt vmcnt(7)
	v_lshlrev_b32_e32 v34, 16, v78
	v_add_f32_e32 v30, v30, v34
	v_and_b32_e32 v34, 0xffff0000, v78
	v_add_f32_e32 v31, v31, v34
	v_lshlrev_b32_e32 v34, 16, v79
	v_add_f32_e32 v32, v32, v34
	v_and_b32_e32 v34, 0xffff0000, v79
	v_add_f32_e32 v33, v33, v34
	v_lshlrev_b32_e32 v34, 16, v80
	v_add_f32_e32 v34, v26, v34
	v_and_b32_e32 v26, 0xffff0000, v80
	s_waitcnt lgkmcnt(0)
	v_add_f32_e32 v35, v27, v26
	v_lshlrev_b32_e32 v26, 16, v81
	v_add_f32_e32 v36, v28, v26
	v_and_b32_e32 v26, 0xffff0000, v81
	v_add_f32_e32 v37, v29, v26
	v_cvt_pk_bf16_f32 v26, v30, v31
	v_mul_f32_e32 v31, v31, v31
	v_fmac_f32_e32 v31, v30, v30
	v_mul_f32_e32 v30, v33, v33
	v_fmac_f32_e32 v30, v32, v32
	v_add_f32_e32 v30, v31, v30
	v_mul_f32_e32 v31, v35, v35
	v_fmac_f32_e32 v31, v34, v34
	v_add_f32_e32 v30, v31, v30
	v_mul_f32_e32 v31, v37, v37
	v_fmac_f32_e32 v31, v36, v36
	v_add_f32_e32 v30, v31, v30
	s_waitcnt vmcnt(6)
	v_lshlrev_b32_e32 v31, 16, v74
	v_add_f32_e32 v22, v22, v31
	v_and_b32_e32 v31, 0xffff0000, v74
	v_add_f32_e32 v23, v23, v31
	v_lshlrev_b32_e32 v31, 16, v75
	v_add_f32_e32 v31, v24, v31
	v_and_b32_e32 v24, 0xffff0000, v75
	v_cvt_pk_bf16_f32 v27, v32, v33
	v_add_f32_e32 v32, v25, v24
	v_lshlrev_b32_e32 v24, 16, v76
	v_add_f32_e32 v33, v18, v24
	v_and_b32_e32 v18, 0xffff0000, v76
	v_cvt_pk_bf16_f32 v28, v34, v35
	v_add_f32_e32 v34, v19, v18
	v_lshlrev_b32_e32 v18, 16, v77
	v_add_f32_e32 v35, v20, v18
	v_and_b32_e32 v18, 0xffff0000, v77
	v_cvt_pk_bf16_f32 v29, v36, v37
	v_add_f32_e32 v36, v21, v18
	v_mul_f32_e32 v18, v23, v23
	v_mul_f32_e32 v19, v32, v32
	v_fmac_f32_e32 v18, v22, v22
	v_fmac_f32_e32 v19, v31, v31
	v_add_f32_e32 v18, v18, v19
	v_mul_f32_e32 v19, v34, v34
	v_fmac_f32_e32 v19, v33, v33
	v_add_f32_e32 v18, v19, v18
	v_mul_f32_e32 v19, v36, v36
	v_fmac_f32_e32 v19, v35, v35
	v_add_f32_e32 v18, v19, v18
	v_add_f32_e32 v21, v30, v18
	ds_bpermute_b32 v30, v140, v21
	v_readlane_b32 s0, v254, 43
	v_readlane_b32 s1, v254, 44
	v_cvt_pk_bf16_f32 v20, v22, v23
	v_cvt_pk_bf16_f32 v22, v33, v34
	v_cvt_pk_bf16_f32 v23, v35, v36
	s_nop 1
	v_lshl_add_u64 v[18:19], s[0:1], 0, v[96:97]
	v_lshl_add_u64 v[24:25], v[174:175], 1, v[18:19]
	s_waitcnt lgkmcnt(0)
	v_add_f32_e32 v18, v21, v30
	ds_bpermute_b32 v19, v141, v18
	global_store_dwordx4 v[24:25], v[26:29], off nt
	v_cvt_pk_bf16_f32 v21, v31, v32
	global_store_dwordx4 v[24:25], v[20:23], off offset:256 nt
	s_and_saveexec_b64 s[0:1], s[40:41]
	s_cbranch_execz .LBB0_179
	s_waitcnt lgkmcnt(0)
	v_add_f32_e32 v18, v18, v19
	v_mul_f32_e32 v18, 0x4b800000, v18
	v_rndne_f32_e32 v18, v18
	v_mul_f32_e32 v19, 0x2f800000, v18
	v_floor_f32_e32 v19, v19
	v_fmac_f32_e32 v18, 0xcf800000, v19
	v_cvt_u32_f32_e32 v18, v18
	v_cvt_u32_f32_e32 v19, v19
	global_atomic_add_x2 v[138:139], v[18:19], off offset:1280
.LBB0_179:
	s_or_b64 exec, exec, s[0:1]
	s_waitcnt vmcnt(7)
	v_lshlrev_b32_e32 v18, 16, v70
	v_add_f32_e32 v14, v14, v18
	v_and_b32_e32 v18, 0xffff0000, v70
	v_add_f32_e32 v15, v15, v18
	v_lshlrev_b32_e32 v18, 16, v71
	v_add_f32_e32 v16, v16, v18
	v_and_b32_e32 v18, 0xffff0000, v71
	v_add_f32_e32 v17, v17, v18
	v_lshlrev_b32_e32 v18, 16, v72
	v_add_f32_e32 v18, v10, v18
	v_and_b32_e32 v10, 0xffff0000, v72
	s_waitcnt lgkmcnt(0)
	v_add_f32_e32 v19, v11, v10
	v_lshlrev_b32_e32 v10, 16, v73
	v_add_f32_e32 v20, v12, v10
	v_and_b32_e32 v10, 0xffff0000, v73
	v_add_f32_e32 v21, v13, v10
	v_cvt_pk_bf16_f32 v10, v14, v15
	v_mul_f32_e32 v15, v15, v15
	v_fmac_f32_e32 v15, v14, v14
	v_mul_f32_e32 v14, v17, v17
	v_fmac_f32_e32 v14, v16, v16
	v_add_f32_e32 v14, v15, v14
	v_mul_f32_e32 v15, v19, v19
	v_fmac_f32_e32 v15, v18, v18
	v_add_f32_e32 v14, v15, v14
	v_mul_f32_e32 v15, v21, v21
	v_fmac_f32_e32 v15, v20, v20
	v_add_f32_e32 v14, v15, v14
	s_waitcnt vmcnt(6)
	v_lshlrev_b32_e32 v15, 16, v66
	v_add_f32_e32 v6, v6, v15
	v_and_b32_e32 v15, 0xffff0000, v66
	v_add_f32_e32 v7, v7, v15
	v_lshlrev_b32_e32 v15, 16, v67
	v_add_f32_e32 v15, v8, v15
	v_and_b32_e32 v8, 0xffff0000, v67
	v_cvt_pk_bf16_f32 v11, v16, v17
	v_add_f32_e32 v16, v9, v8
	v_lshlrev_b32_e32 v8, 16, v68
	v_add_f32_e32 v17, v2, v8
	v_and_b32_e32 v2, 0xffff0000, v68
	v_cvt_pk_bf16_f32 v12, v18, v19
	v_add_f32_e32 v18, v3, v2
	v_lshlrev_b32_e32 v2, 16, v69
	v_add_f32_e32 v19, v4, v2
	v_and_b32_e32 v2, 0xffff0000, v69
	v_cvt_pk_bf16_f32 v13, v20, v21
	v_add_f32_e32 v20, v5, v2
	v_mul_f32_e32 v2, v7, v7
	v_mul_f32_e32 v3, v16, v16
	v_fmac_f32_e32 v2, v6, v6
	v_fmac_f32_e32 v3, v15, v15
	v_add_f32_e32 v2, v2, v3
	v_mul_f32_e32 v3, v18, v18
	v_fmac_f32_e32 v3, v17, v17
	v_add_f32_e32 v2, v3, v2
	v_mul_f32_e32 v3, v20, v20
	v_fmac_f32_e32 v3, v19, v19
	v_add_f32_e32 v2, v3, v2
	v_add_f32_e32 v5, v14, v2
	ds_bpermute_b32 v14, v140, v5
	v_readlane_b32 s0, v254, 43
	v_readlane_b32 s1, v254, 44
	v_cvt_pk_bf16_f32 v4, v6, v7
	v_cvt_pk_bf16_f32 v6, v17, v18
	v_cvt_pk_bf16_f32 v7, v19, v20
	s_nop 1
	v_lshl_add_u64 v[2:3], s[0:1], 0, v[94:95]
	v_lshl_add_u64 v[8:9], v[174:175], 1, v[2:3]
	s_waitcnt lgkmcnt(0)
	v_add_f32_e32 v2, v5, v14
	ds_bpermute_b32 v3, v141, v2
	global_store_dwordx4 v[8:9], v[10:13], off nt
	v_cvt_pk_bf16_f32 v5, v15, v16
	global_store_dwordx4 v[8:9], v[4:7], off offset:256 nt
	s_and_saveexec_b64 s[0:1], s[40:41]
	s_cbranch_execz .LBB0_181
	s_waitcnt lgkmcnt(0)
	v_add_f32_e32 v2, v2, v3
	v_mul_f32_e32 v2, 0x4b800000, v2
	v_rndne_f32_e32 v2, v2
	v_mul_f32_e32 v3, 0x2f800000, v2
	v_floor_f32_e32 v3, v3
	v_fmac_f32_e32 v2, 0xcf800000, v3
	v_cvt_u32_f32_e32 v2, v2
	v_cvt_u32_f32_e32 v3, v3
	global_atomic_add_x2 v[138:139], v[2:3], off offset:1408

.LBB0_217:
	s_waitcnt vmcnt(0)
	v_cvt_f32_ubyte1_e32 v195, v192
	v_cvt_f32_ubyte0_e32 v194, v192
	v_cvt_f32_ubyte3_e32 v197, v192
	v_cvt_f32_ubyte2_e32 v196, v192
	v_lshlrev_b64 v[206:207], 11, v[158:159]
	v_pk_mul_f32 v[198:199], v[122:123], v[194:195]
	v_cvt_f32_ubyte1_e32 v195, v193
	v_cvt_f32_ubyte0_e32 v194, v193
	v_pk_mul_f32 v[200:201], v[124:125], v[196:197]
	v_cvt_f32_ubyte3_e32 v197, v193
	v_cvt_f32_ubyte2_e32 v196, v193
	v_pk_mul_f32 v[194:195], v[126:127], v[194:195]
	v_pk_mul_f32 v[196:197], v[128:129], v[196:197]
	s_mov_b64 s[2:3], -1
	s_and_b64 vcc, exec, s[0:1]
	v_lshl_add_u64 v[192:193], s[36:37], 0, v[206:207]
	v_lshlrev_b32_e32 v0, 1, v0
	s_cbranch_vccz .LBB0_219
	s_mov_b32 s2, 0x3b808081
	v_pk_mul_f32 v[206:207], v[200:201], s[2:3] op_sel_hi:[1,0]
	v_pk_mul_f32 v[224:225], v[198:199], s[2:3] op_sel_hi:[1,0]
	v_pk_mul_f32 v[226:227], v[194:195], s[2:3] op_sel_hi:[1,0]
	v_cvt_pk_bf16_f32 v224, v224, v225
	v_cvt_pk_bf16_f32 v225, v206, v207
	v_lshl_add_u64 v[206:207], v[192:193], 0, v[0:1]
	v_pk_mul_f32 v[228:229], v[196:197], s[2:3] op_sel_hi:[1,0]
	v_cvt_pk_bf16_f32 v226, v226, v227
	s_mov_b64 s[2:3], 0
	v_cvt_pk_bf16_f32 v227, v228, v229
	global_store_dwordx4 v[206:207], v[224:227], off nt

.LBB0_221:
	v_cvt_f32_ubyte1_e32 v195, v190
	v_cvt_f32_ubyte0_e32 v194, v190
	v_pk_mul_f32 v[196:197], v[90:91], v[194:195]
	v_cvt_f32_ubyte1_e32 v195, v191
	v_cvt_f32_ubyte0_e32 v194, v191
	v_cvt_f32_ubyte3_e32 v199, v190
	v_cvt_f32_ubyte2_e32 v198, v190
	v_cvt_f32_ubyte3_e32 v201, v191
	v_cvt_f32_ubyte2_e32 v200, v191
	v_cndmask_b32_e64 v159, 0, 1, s[0:1]
	v_pk_mul_f32 v[194:195], v[94:95], v[194:195]
	v_pk_mul_f32 v[198:199], v[92:93], v[198:199]
	v_pk_mul_f32 v[190:191], v[96:97], v[200:201]
	v_cmp_ne_u32_e64 s[42:43], 1, v159
	s_andn2_b64 vcc, exec, s[0:1]
	s_mov_b64 s[0:1], -1
	s_cbranch_vccnz .LBB0_223
	s_mov_b32 s0, 0x3b808081
	v_pk_mul_f32 v[200:201], v[198:199], s[0:1] op_sel_hi:[1,0]
	v_pk_mul_f32 v[206:207], v[196:197], s[0:1] op_sel_hi:[1,0]
	v_pk_mul_f32 v[228:229], v[190:191], s[0:1] op_sel_hi:[1,0]
	v_pk_mul_f32 v[226:227], v[194:195], s[0:1] op_sel_hi:[1,0]
	v_lshl_add_u64 v[192:193], v[192:193], 0, v[0:1]
	s_mov_b64 s[0:1], 0
	v_cvt_pk_bf16_f32 v224, v206, v207
	v_cvt_pk_bf16_f32 v225, v200, v201
	v_cvt_pk_bf16_f32 v226, v226, v227
	v_cvt_pk_bf16_f32 v227, v228, v229
	global_store_dwordx4 v[192:193], v[224:227], off offset:256 nt

.LBB0_225:
	v_ashrrev_i32_e32 v189, 31, v188
	v_lshlrev_b64 v[196:197], 11, v[188:189]
	v_cvt_f32_ubyte1_e32 v189, v186
	v_cvt_f32_ubyte0_e32 v188, v186
	v_cvt_f32_ubyte3_e32 v191, v186
	v_cvt_f32_ubyte2_e32 v190, v186
	v_pk_mul_f32 v[192:193], v[114:115], v[188:189]
	v_cvt_f32_ubyte1_e32 v189, v187
	v_cvt_f32_ubyte0_e32 v188, v187
	v_pk_mul_f32 v[194:195], v[116:117], v[190:191]
	v_cvt_f32_ubyte3_e32 v191, v187
	v_cvt_f32_ubyte2_e32 v190, v187
	v_pk_mul_f32 v[188:189], v[118:119], v[188:189]
	v_pk_mul_f32 v[190:191], v[120:121], v[190:191]
	s_mov_b64 s[0:1], -1
	s_and_b64 vcc, exec, s[42:43]
	v_lshl_add_u64 v[186:187], s[36:37], 0, v[196:197]
	s_cbranch_vccnz .LBB0_227
	s_mov_b32 s0, 0x3b808081
	v_pk_mul_f32 v[198:199], v[194:195], s[0:1] op_sel_hi:[1,0]
	v_pk_mul_f32 v[196:197], v[192:193], s[0:1] op_sel_hi:[1,0]
	v_pk_mul_f32 v[200:201], v[190:191], s[0:1] op_sel_hi:[1,0]
	v_pk_mul_f32 v[206:207], v[188:189], s[0:1] op_sel_hi:[1,0]
	v_cvt_pk_bf16_f32 v196, v196, v197
	v_cvt_pk_bf16_f32 v197, v198, v199
	v_cvt_pk_bf16_f32 v199, v200, v201
	v_lshl_add_u64 v[200:201], v[186:187], 0, v[0:1]
	s_mov_b64 s[0:1], 0
	v_cvt_pk_bf16_f32 v198, v206, v207
	global_store_dwordx4 v[200:201], v[196:199], off nt

.LBB0_229:
	v_cvt_f32_ubyte1_e32 v189, v184
	v_cvt_f32_ubyte0_e32 v188, v184
	v_pk_mul_f32 v[190:191], v[82:83], v[188:189]
	v_cvt_f32_ubyte1_e32 v189, v185
	v_cvt_f32_ubyte0_e32 v188, v185
	v_cvt_f32_ubyte3_e32 v193, v184
	v_cvt_f32_ubyte2_e32 v192, v184
	v_cvt_f32_ubyte3_e32 v195, v185
	v_cvt_f32_ubyte2_e32 v194, v185
	v_pk_mul_f32 v[188:189], v[86:87], v[188:189]
	v_pk_mul_f32 v[192:193], v[84:85], v[192:193]
	v_pk_mul_f32 v[184:185], v[88:89], v[194:195]
	s_and_b64 vcc, exec, s[42:43]
	s_mov_b64 s[0:1], -1
	s_cbranch_vccnz .LBB0_231
	s_mov_b32 s0, 0x3b808081
	v_pk_mul_f32 v[196:197], v[192:193], s[0:1] op_sel_hi:[1,0]
	v_pk_mul_f32 v[194:195], v[190:191], s[0:1] op_sel_hi:[1,0]
	v_pk_mul_f32 v[198:199], v[184:185], s[0:1] op_sel_hi:[1,0]
	v_pk_mul_f32 v[200:201], v[188:189], s[0:1] op_sel_hi:[1,0]
	v_lshl_add_u64 v[186:187], v[186:187], 0, v[0:1]
	s_mov_b64 s[0:1], 0
	v_cvt_pk_bf16_f32 v194, v194, v195
	v_cvt_pk_bf16_f32 v195, v196, v197
	v_cvt_pk_bf16_f32 v196, v200, v201
	v_cvt_pk_bf16_f32 v197, v198, v199
	global_store_dwordx4 v[186:187], v[194:197], off offset:256 nt

.LBB0_233:
	v_ashrrev_i32_e32 v183, 31, v182
	v_lshlrev_b64 v[190:191], 11, v[182:183]
	v_cvt_f32_ubyte1_e32 v183, v180
	v_cvt_f32_ubyte0_e32 v182, v180
	v_cvt_f32_ubyte3_e32 v185, v180
	v_cvt_f32_ubyte2_e32 v184, v180
	v_pk_mul_f32 v[186:187], v[106:107], v[182:183]
	v_cvt_f32_ubyte1_e32 v183, v181
	v_cvt_f32_ubyte0_e32 v182, v181
	v_pk_mul_f32 v[188:189], v[108:109], v[184:185]
	v_cvt_f32_ubyte3_e32 v185, v181
	v_cvt_f32_ubyte2_e32 v184, v181
	v_pk_mul_f32 v[182:183], v[110:111], v[182:183]
	v_pk_mul_f32 v[184:185], v[112:113], v[184:185]
	s_mov_b64 s[0:1], -1
	s_and_b64 vcc, exec, s[42:43]
	v_lshl_add_u64 v[180:181], s[36:37], 0, v[190:191]
	s_cbranch_vccnz .LBB0_235
	s_mov_b32 s0, 0x3b808081
	v_pk_mul_f32 v[192:193], v[188:189], s[0:1] op_sel_hi:[1,0]
	v_pk_mul_f32 v[190:191], v[186:187], s[0:1] op_sel_hi:[1,0]
	v_pk_mul_f32 v[194:195], v[184:185], s[0:1] op_sel_hi:[1,0]
	v_pk_mul_f32 v[196:197], v[182:183], s[0:1] op_sel_hi:[1,0]
	v_cvt_pk_bf16_f32 v190, v190, v191
	v_cvt_pk_bf16_f32 v191, v192, v193
	v_cvt_pk_bf16_f32 v193, v194, v195
	v_lshl_add_u64 v[194:195], v[180:181], 0, v[0:1]
	s_mov_b64 s[0:1], 0
	v_cvt_pk_bf16_f32 v192, v196, v197
	global_store_dwordx4 v[194:195], v[190:193], off nt

.LBB0_237:
	v_cvt_f32_ubyte1_e32 v183, v178
	v_cvt_f32_ubyte0_e32 v182, v178
	v_pk_mul_f32 v[184:185], v[74:75], v[182:183]
	v_cvt_f32_ubyte1_e32 v183, v179
	v_cvt_f32_ubyte0_e32 v182, v179
	v_cvt_f32_ubyte3_e32 v187, v178
	v_cvt_f32_ubyte2_e32 v186, v178
	v_cvt_f32_ubyte3_e32 v189, v179
	v_cvt_f32_ubyte2_e32 v188, v179
	v_pk_mul_f32 v[182:183], v[78:79], v[182:183]
	v_pk_mul_f32 v[186:187], v[76:77], v[186:187]
	v_pk_mul_f32 v[178:179], v[80:81], v[188:189]
	s_and_b64 vcc, exec, s[42:43]
	s_mov_b64 s[0:1], -1
	s_cbranch_vccnz .LBB0_239
	s_mov_b32 s0, 0x3b808081
	v_pk_mul_f32 v[190:191], v[186:187], s[0:1] op_sel_hi:[1,0]
	v_pk_mul_f32 v[188:189], v[184:185], s[0:1] op_sel_hi:[1,0]
	v_pk_mul_f32 v[192:193], v[178:179], s[0:1] op_sel_hi:[1,0]
	v_pk_mul_f32 v[194:195], v[182:183], s[0:1] op_sel_hi:[1,0]
	v_lshl_add_u64 v[180:181], v[180:181], 0, v[0:1]
	s_mov_b64 s[0:1], 0
	v_cvt_pk_bf16_f32 v188, v188, v189
	v_cvt_pk_bf16_f32 v189, v190, v191
	v_cvt_pk_bf16_f32 v190, v194, v195
	v_cvt_pk_bf16_f32 v191, v192, v193
	global_store_dwordx4 v[180:181], v[188:191], off offset:256 nt

.LBB0_241:
	v_ashrrev_i32_e32 v177, 31, v176
	v_lshlrev_b64 v[184:185], 11, v[176:177]
	v_cvt_f32_ubyte1_e32 v177, v174
	v_cvt_f32_ubyte0_e32 v176, v174
	v_cvt_f32_ubyte3_e32 v179, v174
	v_cvt_f32_ubyte2_e32 v178, v174
	v_pk_mul_f32 v[180:181], v[98:99], v[176:177]
	v_cvt_f32_ubyte1_e32 v177, v175
	v_cvt_f32_ubyte0_e32 v176, v175
	v_pk_mul_f32 v[182:183], v[100:101], v[178:179]
	v_cvt_f32_ubyte3_e32 v179, v175
	v_cvt_f32_ubyte2_e32 v178, v175
	v_pk_mul_f32 v[176:177], v[102:103], v[176:177]
	v_pk_mul_f32 v[178:179], v[104:105], v[178:179]
	s_mov_b64 s[0:1], -1
	s_and_b64 vcc, exec, s[42:43]
	v_lshl_add_u64 v[174:175], s[36:37], 0, v[184:185]
	s_cbranch_vccnz .LBB0_243
	s_mov_b32 s0, 0x3b808081
	v_pk_mul_f32 v[186:187], v[182:183], s[0:1] op_sel_hi:[1,0]
	v_pk_mul_f32 v[184:185], v[180:181], s[0:1] op_sel_hi:[1,0]
	v_pk_mul_f32 v[188:189], v[178:179], s[0:1] op_sel_hi:[1,0]
	v_pk_mul_f32 v[190:191], v[176:177], s[0:1] op_sel_hi:[1,0]
	v_cvt_pk_bf16_f32 v184, v184, v185
	v_cvt_pk_bf16_f32 v185, v186, v187
	v_cvt_pk_bf16_f32 v187, v188, v189
	v_lshl_add_u64 v[188:189], v[174:175], 0, v[0:1]
	s_mov_b64 s[0:1], 0
	v_cvt_pk_bf16_f32 v186, v190, v191
	global_store_dwordx4 v[188:189], v[184:187], off nt

.LBB0_245:
	v_cvt_f32_ubyte1_e32 v177, v172
	v_cvt_f32_ubyte0_e32 v176, v172
	v_pk_mul_f32 v[178:179], v[66:67], v[176:177]
	v_cvt_f32_ubyte1_e32 v177, v173
	v_cvt_f32_ubyte0_e32 v176, v173
	v_cvt_f32_ubyte3_e32 v181, v172
	v_cvt_f32_ubyte2_e32 v180, v172
	v_cvt_f32_ubyte3_e32 v183, v173
	v_cvt_f32_ubyte2_e32 v182, v173
	v_pk_mul_f32 v[176:177], v[70:71], v[176:177]
	v_pk_mul_f32 v[180:181], v[68:69], v[180:181]
	v_pk_mul_f32 v[172:173], v[72:73], v[182:183]
	s_and_b64 vcc, exec, s[42:43]
	s_mov_b64 s[0:1], -1
	s_cbranch_vccnz .LBB0_247
	s_mov_b32 s0, 0x3b808081
	v_pk_mul_f32 v[184:185], v[180:181], s[0:1] op_sel_hi:[1,0]
	v_pk_mul_f32 v[182:183], v[178:179], s[0:1] op_sel_hi:[1,0]
	v_pk_mul_f32 v[186:187], v[172:173], s[0:1] op_sel_hi:[1,0]
	v_pk_mul_f32 v[188:189], v[176:177], s[0:1] op_sel_hi:[1,0]
	v_lshl_add_u64 v[174:175], v[174:175], 0, v[0:1]
	s_mov_b64 s[0:1], 0
	v_cvt_pk_bf16_f32 v182, v182, v183
	v_cvt_pk_bf16_f32 v183, v184, v185
	v_cvt_pk_bf16_f32 v184, v188, v189
	v_cvt_pk_bf16_f32 v185, v186, v187
	global_store_dwordx4 v[174:175], v[182:185], off offset:256 nt

.LBB0_265:
	v_ashrrev_i32_e32 v191, 31, v190
	v_lshlrev_b64 v[198:199], 11, v[190:191]
	s_waitcnt vmcnt(7)
	v_cvt_f32_ubyte1_e32 v191, v188
	v_cvt_f32_ubyte0_e32 v190, v188
	v_cvt_f32_ubyte1_e32 v193, v189
	v_cvt_f32_ubyte0_e32 v192, v189
	v_cvt_f32_ubyte3_e32 v195, v188
	v_cvt_f32_ubyte2_e32 v194, v188
	v_cvt_f32_ubyte3_e32 v197, v189
	v_cvt_f32_ubyte2_e32 v196, v189
	v_pk_mul_f32 v[190:191], v[62:63], v[190:191]
	v_pk_mul_f32 v[192:193], v[58:59], v[192:193]
	v_pk_mul_f32 v[194:195], v[64:65], v[194:195]
	v_pk_mul_f32 v[196:197], v[60:61], v[196:197]
	s_mov_b64 s[0:1], -1
	s_and_b64 vcc, exec, s[42:43]
	v_lshl_add_u64 v[188:189], s[36:37], 0, v[198:199]
	s_cbranch_vccnz .LBB0_267
	s_mov_b32 s0, 0x3b808081
	v_pk_mul_f32 v[200:201], v[194:195], s[0:1] op_sel_hi:[1,0]
	v_pk_mul_f32 v[198:199], v[190:191], s[0:1] op_sel_hi:[1,0]
	v_pk_mul_f32 v[206:207], v[196:197], s[0:1] op_sel_hi:[1,0]
	v_pk_mul_f32 v[224:225], v[192:193], s[0:1] op_sel_hi:[1,0]
	v_cvt_pk_bf16_f32 v198, v198, v199
	v_cvt_pk_bf16_f32 v199, v200, v201
	v_cvt_pk_bf16_f32 v201, v206, v207
	v_lshl_add_u64 v[206:207], v[188:189], 0, v[0:1]
	s_mov_b64 s[0:1], 0
	v_cvt_pk_bf16_f32 v200, v224, v225
	global_store_dwordx4 v[206:207], v[198:201], off nt

.LBB0_269:
	s_waitcnt vmcnt(6)
	v_cvt_f32_ubyte1_e32 v157, v186
	v_cvt_f32_ubyte0_e32 v156, v186
	v_cvt_f32_ubyte1_e32 v191, v187
	v_cvt_f32_ubyte0_e32 v190, v187
	v_cvt_f32_ubyte3_e32 v193, v186
	v_cvt_f32_ubyte2_e32 v192, v186
	v_cvt_f32_ubyte3_e32 v195, v187
	v_cvt_f32_ubyte2_e32 v194, v187
	v_pk_mul_f32 v[156:157], v[30:31], v[156:157]
	v_pk_mul_f32 v[190:191], v[26:27], v[190:191]
	v_pk_mul_f32 v[192:193], v[32:33], v[192:193]
	v_pk_mul_f32 v[186:187], v[28:29], v[194:195]
	s_and_b64 vcc, exec, s[42:43]
	s_mov_b64 s[0:1], -1
	s_cbranch_vccnz .LBB0_271
	s_mov_b32 s0, 0x3b808081
	v_pk_mul_f32 v[196:197], v[192:193], s[0:1] op_sel_hi:[1,0]
	v_pk_mul_f32 v[194:195], v[156:157], s[0:1] op_sel_hi:[1,0]
	v_pk_mul_f32 v[198:199], v[186:187], s[0:1] op_sel_hi:[1,0]
	v_pk_mul_f32 v[200:201], v[190:191], s[0:1] op_sel_hi:[1,0]
	v_lshl_add_u64 v[188:189], v[188:189], 0, v[0:1]
	s_mov_b64 s[0:1], 0
	v_cvt_pk_bf16_f32 v194, v194, v195
	v_cvt_pk_bf16_f32 v195, v196, v197
	v_cvt_pk_bf16_f32 v196, v200, v201
	v_cvt_pk_bf16_f32 v197, v198, v199
	global_store_dwordx4 v[188:189], v[194:197], off offset:256 nt

.LBB0_273:
	v_ashrrev_i32_e32 v185, 31, v184
	v_lshlrev_b64 v[154:155], 11, v[184:185]
	s_waitcnt vmcnt(5)
	v_cvt_f32_ubyte1_e32 v157, v182
	v_cvt_f32_ubyte0_e32 v156, v182
	v_cvt_f32_ubyte1_e32 v185, v183
	v_cvt_f32_ubyte0_e32 v184, v183
	v_cvt_f32_ubyte3_e32 v187, v182
	v_cvt_f32_ubyte2_e32 v186, v182
	v_cvt_f32_ubyte3_e32 v189, v183
	v_cvt_f32_ubyte2_e32 v188, v183
	v_pk_mul_f32 v[156:157], v[54:55], v[156:157]
	v_pk_mul_f32 v[184:185], v[50:51], v[184:185]
	v_pk_mul_f32 v[186:187], v[56:57], v[186:187]
	v_pk_mul_f32 v[182:183], v[52:53], v[188:189]
	s_mov_b64 s[0:1], -1
	s_and_b64 vcc, exec, s[42:43]
	v_lshl_add_u64 v[154:155], s[36:37], 0, v[154:155]
	s_cbranch_vccnz .LBB0_275
	s_mov_b32 s0, 0x3b808081
	v_pk_mul_f32 v[190:191], v[186:187], s[0:1] op_sel_hi:[1,0]
	v_pk_mul_f32 v[188:189], v[156:157], s[0:1] op_sel_hi:[1,0]
	v_pk_mul_f32 v[192:193], v[182:183], s[0:1] op_sel_hi:[1,0]
	v_pk_mul_f32 v[194:195], v[184:185], s[0:1] op_sel_hi:[1,0]
	v_cvt_pk_bf16_f32 v188, v188, v189
	v_cvt_pk_bf16_f32 v189, v190, v191
	v_cvt_pk_bf16_f32 v191, v192, v193
	v_lshl_add_u64 v[192:193], v[154:155], 0, v[0:1]
	s_mov_b64 s[0:1], 0
	v_cvt_pk_bf16_f32 v190, v194, v195
	global_store_dwordx4 v[192:193], v[188:191], off nt

.LBB0_277:
	s_waitcnt vmcnt(4)
	v_cvt_f32_ubyte1_e32 v153, v180
	v_cvt_f32_ubyte0_e32 v152, v180
	v_cvt_f32_ubyte1_e32 v157, v181
	v_cvt_f32_ubyte0_e32 v156, v181
	v_cvt_f32_ubyte3_e32 v183, v180
	v_cvt_f32_ubyte2_e32 v182, v180
	v_cvt_f32_ubyte3_e32 v185, v181
	v_cvt_f32_ubyte2_e32 v184, v181
	v_pk_mul_f32 v[152:153], v[22:23], v[152:153]
	v_pk_mul_f32 v[156:157], v[18:19], v[156:157]
	v_pk_mul_f32 v[182:183], v[24:25], v[182:183]
	v_pk_mul_f32 v[180:181], v[20:21], v[184:185]
	s_and_b64 vcc, exec, s[42:43]
	s_mov_b64 s[0:1], -1
	s_cbranch_vccnz .LBB0_279
	s_mov_b32 s0, 0x3b808081
	v_pk_mul_f32 v[186:187], v[182:183], s[0:1] op_sel_hi:[1,0]
	v_pk_mul_f32 v[184:185], v[152:153], s[0:1] op_sel_hi:[1,0]
	v_pk_mul_f32 v[188:189], v[180:181], s[0:1] op_sel_hi:[1,0]
	v_pk_mul_f32 v[190:191], v[156:157], s[0:1] op_sel_hi:[1,0]
	v_lshl_add_u64 v[154:155], v[154:155], 0, v[0:1]
	s_mov_b64 s[0:1], 0
	v_cvt_pk_bf16_f32 v184, v184, v185
	v_cvt_pk_bf16_f32 v185, v186, v187
	v_cvt_pk_bf16_f32 v186, v190, v191
	v_cvt_pk_bf16_f32 v187, v188, v189
	global_store_dwordx4 v[154:155], v[184:187], off offset:256 nt

.LBB0_281:
	v_ashrrev_i32_e32 v179, 31, v178
	v_lshlrev_b64 v[150:151], 11, v[178:179]
	s_waitcnt vmcnt(3)
	v_cvt_f32_ubyte1_e32 v153, v176
	v_cvt_f32_ubyte0_e32 v152, v176
	v_cvt_f32_ubyte1_e32 v155, v177
	v_cvt_f32_ubyte0_e32 v154, v177
	v_cvt_f32_ubyte3_e32 v157, v176
	v_cvt_f32_ubyte2_e32 v156, v176
	v_cvt_f32_ubyte3_e32 v179, v177
	v_cvt_f32_ubyte2_e32 v178, v177
	v_pk_mul_f32 v[152:153], v[46:47], v[152:153]
	v_pk_mul_f32 v[154:155], v[42:43], v[154:155]
	v_pk_mul_f32 v[156:157], v[48:49], v[156:157]
	v_pk_mul_f32 v[176:177], v[44:45], v[178:179]
	s_mov_b64 s[0:1], -1
	s_and_b64 vcc, exec, s[42:43]
	v_lshl_add_u64 v[150:151], s[36:37], 0, v[150:151]
	s_cbranch_vccnz .LBB0_283
	s_mov_b32 s0, 0x3b808081
	v_pk_mul_f32 v[180:181], v[156:157], s[0:1] op_sel_hi:[1,0]
	v_pk_mul_f32 v[178:179], v[152:153], s[0:1] op_sel_hi:[1,0]
	v_pk_mul_f32 v[182:183], v[176:177], s[0:1] op_sel_hi:[1,0]
	v_pk_mul_f32 v[184:185], v[154:155], s[0:1] op_sel_hi:[1,0]
	v_cvt_pk_bf16_f32 v178, v178, v179
	v_cvt_pk_bf16_f32 v179, v180, v181
	v_cvt_pk_bf16_f32 v181, v182, v183
	v_lshl_add_u64 v[182:183], v[150:151], 0, v[0:1]
	s_mov_b64 s[0:1], 0
	v_cvt_pk_bf16_f32 v180, v184, v185
	global_store_dwordx4 v[182:183], v[178:181], off nt

.LBB0_285:
	s_waitcnt vmcnt(2)
	v_cvt_f32_ubyte1_e32 v149, v174
	v_cvt_f32_ubyte0_e32 v148, v174
	v_cvt_f32_ubyte1_e32 v153, v175
	v_cvt_f32_ubyte0_e32 v152, v175
	v_cvt_f32_ubyte3_e32 v155, v174
	v_cvt_f32_ubyte2_e32 v154, v174
	v_cvt_f32_ubyte3_e32 v157, v175
	v_cvt_f32_ubyte2_e32 v156, v175
	v_pk_mul_f32 v[148:149], v[14:15], v[148:149]
	v_pk_mul_f32 v[152:153], v[10:11], v[152:153]
	v_pk_mul_f32 v[154:155], v[16:17], v[154:155]
	v_pk_mul_f32 v[156:157], v[12:13], v[156:157]
	s_and_b64 vcc, exec, s[42:43]
	s_mov_b64 s[0:1], -1
	s_cbranch_vccnz .LBB0_287
	s_mov_b32 s0, 0x3b808081
	v_pk_mul_f32 v[176:177], v[154:155], s[0:1] op_sel_hi:[1,0]
	v_pk_mul_f32 v[174:175], v[148:149], s[0:1] op_sel_hi:[1,0]
	v_pk_mul_f32 v[178:179], v[156:157], s[0:1] op_sel_hi:[1,0]
	v_pk_mul_f32 v[180:181], v[152:153], s[0:1] op_sel_hi:[1,0]
	v_lshl_add_u64 v[150:151], v[150:151], 0, v[0:1]
	s_mov_b64 s[0:1], 0
	v_cvt_pk_bf16_f32 v174, v174, v175
	v_cvt_pk_bf16_f32 v175, v176, v177
	v_cvt_pk_bf16_f32 v176, v180, v181
	v_cvt_pk_bf16_f32 v177, v178, v179
	global_store_dwordx4 v[150:151], v[174:177], off offset:256 nt

.LBB0_289:
	v_ashrrev_i32_e32 v173, 31, v172
	v_lshlrev_b64 v[146:147], 11, v[172:173]
	s_waitcnt vmcnt(1)
	v_cvt_f32_ubyte1_e32 v149, v170
	v_cvt_f32_ubyte0_e32 v148, v170
	v_cvt_f32_ubyte1_e32 v151, v171
	v_cvt_f32_ubyte0_e32 v150, v171
	v_cvt_f32_ubyte3_e32 v153, v170
	v_cvt_f32_ubyte2_e32 v152, v170
	v_cvt_f32_ubyte3_e32 v155, v171
	v_cvt_f32_ubyte2_e32 v154, v171
	v_pk_mul_f32 v[148:149], v[38:39], v[148:149]
	v_pk_mul_f32 v[150:151], v[34:35], v[150:151]
	v_pk_mul_f32 v[152:153], v[40:41], v[152:153]
	v_pk_mul_f32 v[154:155], v[36:37], v[154:155]
	s_mov_b64 s[0:1], -1
	s_and_b64 vcc, exec, s[42:43]
	v_lshl_add_u64 v[146:147], s[36:37], 0, v[146:147]
	s_cbranch_vccnz .LBB0_291
	s_mov_b32 s0, 0x3b808081
	v_pk_mul_f32 v[156:157], v[152:153], s[0:1] op_sel_hi:[1,0]
	v_pk_mul_f32 v[170:171], v[148:149], s[0:1] op_sel_hi:[1,0]
	v_pk_mul_f32 v[174:175], v[154:155], s[0:1] op_sel_hi:[1,0]
	v_pk_mul_f32 v[172:173], v[150:151], s[0:1] op_sel_hi:[1,0]
	v_cvt_pk_bf16_f32 v170, v170, v171
	v_cvt_pk_bf16_f32 v171, v156, v157
	v_lshl_add_u64 v[156:157], v[146:147], 0, v[0:1]
	s_mov_b64 s[0:1], 0
	v_cvt_pk_bf16_f32 v172, v172, v173
	v_cvt_pk_bf16_f32 v173, v174, v175
	global_store_dwordx4 v[156:157], v[170:173], off nt

.LBB0_293:
	s_waitcnt vmcnt(0)
	v_cvt_f32_ubyte1_e32 v145, v158
	v_cvt_f32_ubyte0_e32 v144, v158
	v_cvt_f32_ubyte1_e32 v149, v159
	v_cvt_f32_ubyte0_e32 v148, v159
	v_cvt_f32_ubyte3_e32 v151, v158
	v_cvt_f32_ubyte2_e32 v150, v158
	v_cvt_f32_ubyte3_e32 v153, v159
	v_cvt_f32_ubyte2_e32 v152, v159
	v_pk_mul_f32 v[144:145], v[6:7], v[144:145]
	v_pk_mul_f32 v[148:149], v[2:3], v[148:149]
	v_pk_mul_f32 v[150:151], v[8:9], v[150:151]
	v_pk_mul_f32 v[152:153], v[4:5], v[152:153]
	s_and_b64 vcc, exec, s[42:43]
	s_mov_b64 s[0:1], -1
	s_cbranch_vccnz .LBB0_296
	s_mov_b32 s0, 0x3b808081
	v_pk_mul_f32 v[156:157], v[150:151], s[0:1] op_sel_hi:[1,0]
	v_pk_mul_f32 v[154:155], v[144:145], s[0:1] op_sel_hi:[1,0]
	v_pk_mul_f32 v[158:159], v[152:153], s[0:1] op_sel_hi:[1,0]
	v_pk_mul_f32 v[170:171], v[148:149], s[0:1] op_sel_hi:[1,0]
	v_lshl_add_u64 v[146:147], v[146:147], 0, v[0:1]
	v_cvt_pk_bf16_f32 v154, v154, v155
	v_cvt_pk_bf16_f32 v155, v156, v157
	v_cvt_pk_bf16_f32 v156, v170, v171
	v_cvt_pk_bf16_f32 v157, v158, v159
	global_store_dwordx4 v[146:147], v[154:157], off offset:256 nt
	s_cbranch_execz .LBB0_297

.LBB0_665:
	v_lshl_or_b32 v174, s24, 8, v190
	v_lshl_add_u32 v186, s23, 8, v188
	v_ashrrev_i32_e32 v175, 31, v174
	v_readlane_b32 s4, v254, 41
	v_lshlrev_b64 v[200:201], 1, v[174:175]
	v_readlane_b32 s5, v254, 42
	v_ashrrev_i32_e32 v187, 31, v186
	v_lshlrev_b64 v[178:179], 11, v[186:187]
	v_lshl_add_u64 v[176:177], s[4:5], 0, v[200:201]
	v_lshl_add_u64 v[114:115], v[176:177], 0, v[178:179]
	global_load_dwordx4 v[192:195], v[114:115], off
	global_load_dwordx4 v[196:199], v[114:115], off offset:256
	v_or_b32_e32 v114, 16, v186
	v_ashrrev_i32_e32 v115, 31, v114
	v_lshlrev_b64 v[184:185], 11, v[114:115]
	v_lshl_add_u64 v[114:115], v[176:177], 0, v[184:185]
	global_load_dwordx4 v[134:137], v[114:115], off
	global_load_dwordx4 v[130:133], v[114:115], off offset:256
	v_or_b32_e32 v114, 32, v186
	v_ashrrev_i32_e32 v115, 31, v114
	v_lshlrev_b64 v[182:183], 11, v[114:115]
	v_lshl_add_u64 v[114:115], v[176:177], 0, v[182:183]
	global_load_dwordx4 v[126:129], v[114:115], off
	global_load_dwordx4 v[122:125], v[114:115], off offset:256
	v_or_b32_e32 v114, 48, v186
	v_ashrrev_i32_e32 v115, 31, v114
	v_lshlrev_b64 v[180:181], 11, v[114:115]
	v_lshl_add_u64 v[114:115], v[176:177], 0, v[180:181]
	global_load_dwordx4 v[118:121], v[114:115], off
	s_nop 0
	global_load_dwordx4 v[114:117], v[114:115], off offset:256
	s_waitcnt vmcnt(0)
	v_lshlrev_b32_e32 v202, 16, v192
	v_add_f32_e32 v202, v150, v202
	v_and_b32_e32 v150, 0xffff0000, v192
	v_add_f32_e32 v192, v151, v150
	v_lshlrev_b32_e32 v150, 16, v193
	v_add_f32_e32 v152, v152, v150
	v_and_b32_e32 v150, 0xffff0000, v193
	v_add_f32_e32 v153, v153, v150
	v_lshlrev_b32_e32 v150, 16, v194
	v_add_f32_e32 v193, v146, v150
	v_and_b32_e32 v146, 0xffff0000, v194
	v_add_f32_e32 v194, v147, v146
	v_lshlrev_b32_e32 v146, 16, v195
	v_add_f32_e32 v203, v148, v146
	v_and_b32_e32 v146, 0xffff0000, v195
	v_lshl_add_u64 v[150:151], s[4:5], 0, v[178:179]
	v_add_f32_e32 v195, v149, v146
	v_cvt_pk_bf16_f32 v146, v202, v192
	v_cvt_pk_bf16_f32 v147, v152, v153
	v_lshl_add_u64 v[150:151], v[150:151], 0, v[200:201]
	v_cvt_pk_bf16_f32 v148, v193, v194
	v_cvt_pk_bf16_f32 v149, v203, v195
	global_store_dwordx4 v[150:151], v[146:149], off nt
	s_nop 1
	v_mul_f32_e32 v146, v192, v192
	v_mul_f32_e32 v147, v153, v153
	v_fmac_f32_e32 v146, v202, v202
	v_fmac_f32_e32 v147, v152, v152
	v_add_f32_e32 v146, v146, v147
	v_mul_f32_e32 v147, v194, v194
	v_fmac_f32_e32 v147, v193, v193
	v_add_f32_e32 v146, v147, v146
	v_mul_f32_e32 v147, v195, v195
	v_fmac_f32_e32 v147, v203, v203
	v_add_f32_e32 v146, v147, v146
	v_lshlrev_b32_e32 v147, 16, v196
	v_add_f32_e32 v142, v142, v147
	v_and_b32_e32 v147, 0xffff0000, v196
	v_add_f32_e32 v143, v143, v147
	v_lshlrev_b32_e32 v147, 16, v197
	v_add_f32_e32 v144, v144, v147
	v_and_b32_e32 v147, 0xffff0000, v197
	v_add_f32_e32 v145, v145, v147
	v_lshlrev_b32_e32 v147, 16, v198
	v_add_f32_e32 v147, v138, v147
	v_and_b32_e32 v138, 0xffff0000, v198
	v_add_f32_e32 v148, v139, v138
	v_lshlrev_b32_e32 v138, 16, v199
	v_add_f32_e32 v149, v140, v138
	v_and_b32_e32 v138, 0xffff0000, v199
	v_add_f32_e32 v152, v141, v138
	v_cvt_pk_bf16_f32 v138, v142, v143
	v_cvt_pk_bf16_f32 v139, v144, v145
	v_cvt_pk_bf16_f32 v140, v147, v148
	v_cvt_pk_bf16_f32 v141, v149, v152
	global_store_dwordx4 v[150:151], v[138:141], off offset:256 nt
	s_nop 1
	v_mul_f32_e32 v138, v143, v143
	v_mul_f32_e32 v139, v145, v145
	v_fmac_f32_e32 v138, v142, v142
	v_fmac_f32_e32 v139, v144, v144
	v_add_f32_e32 v138, v138, v139
	v_mul_f32_e32 v139, v148, v148
	v_fmac_f32_e32 v139, v147, v147
	v_add_f32_e32 v138, v139, v138
	v_mul_f32_e32 v139, v152, v152
	v_fmac_f32_e32 v139, v149, v149
	v_and_b32_e32 v140, 64, v211
	v_add_f32_e32 v138, v139, v138
	v_xor_b32_e32 v139, 16, v211
	v_add_u32_e32 v141, 64, v140
	v_cmp_lt_i32_e32 vcc, v139, v141
	v_add_f32_e32 v138, v146, v138
	s_nop 0
	v_cndmask_b32_e32 v139, v211, v139, vcc
	v_lshlrev_b32_e32 v140, 2, v139
	ds_bpermute_b32 v139, v140, v138
	s_waitcnt lgkmcnt(0)
	v_add_f32_e32 v142, v138, v139
	v_xor_b32_e32 v138, 32, v211
	v_cmp_lt_i32_e32 vcc, v138, v141
	s_nop 1
	v_cndmask_b32_e32 v138, v211, v138, vcc
	v_lshlrev_b32_e32 v141, 2, v138
	ds_bpermute_b32 v143, v141, v142
	v_lshl_add_u64 v[138:139], v[186:187], 3, s[38:39]
	s_and_saveexec_b64 s[0:1], s[40:41]
	s_cbranch_execz .LBB0_667
	s_waitcnt lgkmcnt(0)
	v_add_f32_e32 v142, v142, v143
	v_mul_f32_e32 v142, 0x4b800000, v142
	v_rndne_f32_e32 v142, v142
	v_mul_f32_e32 v143, 0x2f800000, v142
	v_floor_f32_e32 v143, v143
	v_fmac_f32_e32 v142, 0xcf800000, v143
	v_cvt_u32_f32_e32 v142, v142
	v_cvt_u32_f32_e32 v143, v143
	global_atomic_add_x2 v[138:139], v[142:143], off
.LBB0_667:
	s_or_b64 exec, exec, s[0:1]
	v_lshlrev_b32_e32 v142, 16, v134
	v_and_b32_e32 v134, 0xffff0000, v134
	v_add_f32_e32 v111, v111, v134
	v_lshlrev_b32_e32 v134, 16, v135
	v_add_f32_e32 v112, v112, v134
	v_and_b32_e32 v134, 0xffff0000, v135
	v_add_f32_e32 v113, v113, v134
	v_lshlrev_b32_e32 v134, 16, v136
	v_add_f32_e32 v134, v106, v134
	v_and_b32_e32 v106, 0xffff0000, v136
	v_add_f32_e32 v135, v107, v106
	v_lshlrev_b32_e32 v106, 16, v137
	v_add_f32_e32 v136, v108, v106
	v_and_b32_e32 v106, 0xffff0000, v137
	v_add_f32_e32 v110, v110, v142
	v_add_f32_e32 v137, v109, v106
	v_cvt_pk_bf16_f32 v106, v110, v111
	v_mul_f32_e32 v111, v111, v111
	v_fmac_f32_e32 v111, v110, v110
	v_mul_f32_e32 v110, v113, v113
	v_fmac_f32_e32 v110, v112, v112
	v_add_f32_e32 v110, v111, v110
	v_mul_f32_e32 v111, v135, v135
	v_fmac_f32_e32 v111, v134, v134
	v_add_f32_e32 v110, v111, v110
	v_mul_f32_e32 v111, v137, v137
	v_fmac_f32_e32 v111, v136, v136
	v_add_f32_e32 v110, v111, v110
	v_lshlrev_b32_e32 v111, 16, v130
	v_add_f32_e32 v102, v102, v111
	v_and_b32_e32 v111, 0xffff0000, v130
	v_add_f32_e32 v103, v103, v111
	v_lshlrev_b32_e32 v111, 16, v131
	v_add_f32_e32 v111, v104, v111
	v_and_b32_e32 v104, 0xffff0000, v131
	v_cvt_pk_bf16_f32 v107, v112, v113
	v_add_f32_e32 v112, v105, v104
	v_lshlrev_b32_e32 v104, 16, v132
	v_add_f32_e32 v113, v98, v104
	v_and_b32_e32 v98, 0xffff0000, v132
	v_add_f32_e32 v130, v99, v98
	v_lshlrev_b32_e32 v98, 16, v133
	v_add_f32_e32 v131, v100, v98
	v_and_b32_e32 v98, 0xffff0000, v133
	v_add_f32_e32 v132, v101, v98
	v_mul_f32_e32 v98, v103, v103
	v_mul_f32_e32 v99, v112, v112
	v_fmac_f32_e32 v98, v102, v102
	v_fmac_f32_e32 v99, v111, v111
	v_add_f32_e32 v98, v98, v99
	v_mul_f32_e32 v99, v130, v130
	v_fmac_f32_e32 v99, v113, v113
	v_add_f32_e32 v98, v99, v98
	v_mul_f32_e32 v99, v132, v132
	v_fmac_f32_e32 v99, v131, v131
	v_add_f32_e32 v98, v99, v98
	v_add_f32_e32 v101, v110, v98
	ds_bpermute_b32 v110, v140, v101
	v_lshl_add_u64 v[98:99], s[4:5], 0, v[184:185]
	v_lshl_add_u64 v[104:105], v[174:175], 1, v[98:99]
	v_cvt_pk_bf16_f32 v108, v134, v135
	v_cvt_pk_bf16_f32 v109, v136, v137
	s_waitcnt lgkmcnt(0)
	v_add_f32_e32 v98, v101, v110
	ds_bpermute_b32 v99, v141, v98
	global_store_dwordx4 v[104:105], v[106:109], off nt
	v_cvt_pk_bf16_f32 v100, v102, v103
	v_cvt_pk_bf16_f32 v101, v111, v112
	v_cvt_pk_bf16_f32 v102, v113, v130
	v_cvt_pk_bf16_f32 v103, v131, v132
	global_store_dwordx4 v[104:105], v[100:103], off offset:256 nt
	s_and_saveexec_b64 s[0:1], s[40:41]
	s_cbranch_execz .LBB0_669
	s_waitcnt lgkmcnt(0)
	v_add_f32_e32 v98, v98, v99
	v_mul_f32_e32 v98, 0x4b800000, v98
	v_rndne_f32_e32 v98, v98
	v_mul_f32_e32 v99, 0x2f800000, v98
	v_floor_f32_e32 v99, v99
	v_fmac_f32_e32 v98, 0xcf800000, v99
	v_cvt_u32_f32_e32 v98, v98
	v_cvt_u32_f32_e32 v99, v99
	global_atomic_add_x2 v[138:139], v[98:99], off offset:128
.LBB0_669:
	s_or_b64 exec, exec, s[0:1]
	v_lshlrev_b32_e32 v98, 16, v126
	v_add_f32_e32 v94, v94, v98
	v_and_b32_e32 v98, 0xffff0000, v126
	v_add_f32_e32 v95, v95, v98
	v_lshlrev_b32_e32 v98, 16, v127
	v_add_f32_e32 v96, v96, v98
	v_and_b32_e32 v98, 0xffff0000, v127
	v_add_f32_e32 v97, v97, v98
	v_lshlrev_b32_e32 v98, 16, v128
	v_add_f32_e32 v98, v90, v98
	v_and_b32_e32 v90, 0xffff0000, v128
	s_waitcnt lgkmcnt(0)
	v_add_f32_e32 v99, v91, v90
	v_lshlrev_b32_e32 v90, 16, v129
	v_add_f32_e32 v100, v92, v90
	v_and_b32_e32 v90, 0xffff0000, v129
	v_add_f32_e32 v101, v93, v90
	v_cvt_pk_bf16_f32 v90, v94, v95
	v_mul_f32_e32 v95, v95, v95
	v_fmac_f32_e32 v95, v94, v94
	v_mul_f32_e32 v94, v97, v97
	v_fmac_f32_e32 v94, v96, v96
	v_add_f32_e32 v94, v95, v94
	v_mul_f32_e32 v95, v99, v99
	v_fmac_f32_e32 v95, v98, v98
	v_add_f32_e32 v94, v95, v94
	v_mul_f32_e32 v95, v101, v101
	v_fmac_f32_e32 v95, v100, v100
	v_add_f32_e32 v94, v95, v94
	v_lshlrev_b32_e32 v95, 16, v122
	v_add_f32_e32 v86, v86, v95
	v_and_b32_e32 v95, 0xffff0000, v122
	v_add_f32_e32 v87, v87, v95
	v_lshlrev_b32_e32 v95, 16, v123
	v_add_f32_e32 v95, v88, v95
	v_and_b32_e32 v88, 0xffff0000, v123
	v_cvt_pk_bf16_f32 v91, v96, v97
	v_add_f32_e32 v96, v89, v88
	v_lshlrev_b32_e32 v88, 16, v124
	v_add_f32_e32 v97, v82, v88
	v_and_b32_e32 v82, 0xffff0000, v124
	v_cvt_pk_bf16_f32 v92, v98, v99
	v_add_f32_e32 v98, v83, v82
	v_lshlrev_b32_e32 v82, 16, v125
	v_add_f32_e32 v99, v84, v82
	v_and_b32_e32 v82, 0xffff0000, v125
	v_cvt_pk_bf16_f32 v93, v100, v101
	v_add_f32_e32 v100, v85, v82
	v_mul_f32_e32 v82, v87, v87
	v_mul_f32_e32 v83, v96, v96
	v_fmac_f32_e32 v82, v86, v86
	v_fmac_f32_e32 v83, v95, v95
	v_add_f32_e32 v82, v82, v83
	v_mul_f32_e32 v83, v98, v98
	v_fmac_f32_e32 v83, v97, v97
	v_add_f32_e32 v82, v83, v82
	v_mul_f32_e32 v83, v100, v100
	v_fmac_f32_e32 v83, v99, v99
	v_add_f32_e32 v82, v83, v82
	v_add_f32_e32 v85, v94, v82
	ds_bpermute_b32 v94, v140, v85
	v_lshl_add_u64 v[82:83], s[4:5], 0, v[182:183]
	v_lshl_add_u64 v[88:89], v[174:175], 1, v[82:83]
	global_store_dwordx4 v[88:89], v[90:93], off nt
	v_cvt_pk_bf16_f32 v84, v86, v87
	s_waitcnt lgkmcnt(0)
	v_add_f32_e32 v82, v85, v94
	ds_bpermute_b32 v83, v141, v82
	v_cvt_pk_bf16_f32 v85, v95, v96
	v_cvt_pk_bf16_f32 v86, v97, v98
	v_cvt_pk_bf16_f32 v87, v99, v100
	global_store_dwordx4 v[88:89], v[84:87], off offset:256 nt
	s_and_saveexec_b64 s[0:1], s[40:41]
	s_cbranch_execz .LBB0_671
	s_waitcnt lgkmcnt(0)
	v_add_f32_e32 v82, v82, v83
	v_mul_f32_e32 v82, 0x4b800000, v82
	v_rndne_f32_e32 v82, v82
	v_mul_f32_e32 v83, 0x2f800000, v82
	v_floor_f32_e32 v83, v83
	v_fmac_f32_e32 v82, 0xcf800000, v83
	v_cvt_u32_f32_e32 v82, v82
	v_cvt_u32_f32_e32 v83, v83
	global_atomic_add_x2 v[138:139], v[82:83], off offset:256
.LBB0_671:
	s_or_b64 exec, exec, s[0:1]
	v_lshlrev_b32_e32 v82, 16, v118
	v_add_f32_e32 v78, v78, v82
	v_and_b32_e32 v82, 0xffff0000, v118
	v_add_f32_e32 v79, v79, v82
	v_lshlrev_b32_e32 v82, 16, v119
	v_add_f32_e32 v80, v80, v82
	v_and_b32_e32 v82, 0xffff0000, v119
	v_add_f32_e32 v81, v81, v82
	v_lshlrev_b32_e32 v82, 16, v120
	v_add_f32_e32 v82, v74, v82
	v_and_b32_e32 v74, 0xffff0000, v120
	s_waitcnt lgkmcnt(0)
	v_add_f32_e32 v83, v75, v74
	v_lshlrev_b32_e32 v74, 16, v121
	v_add_f32_e32 v84, v76, v74
	v_and_b32_e32 v74, 0xffff0000, v121
	v_add_f32_e32 v85, v77, v74
	v_cvt_pk_bf16_f32 v74, v78, v79
	v_mul_f32_e32 v79, v79, v79
	v_fmac_f32_e32 v79, v78, v78
	v_mul_f32_e32 v78, v81, v81
	v_fmac_f32_e32 v78, v80, v80
	v_add_f32_e32 v78, v79, v78
	v_mul_f32_e32 v79, v83, v83
	v_fmac_f32_e32 v79, v82, v82
	v_add_f32_e32 v78, v79, v78
	v_mul_f32_e32 v79, v85, v85
	v_fmac_f32_e32 v79, v84, v84
	v_add_f32_e32 v78, v79, v78
	v_lshlrev_b32_e32 v79, 16, v114
	v_add_f32_e32 v70, v70, v79
	v_and_b32_e32 v79, 0xffff0000, v114
	v_add_f32_e32 v71, v71, v79
	v_lshlrev_b32_e32 v79, 16, v115
	v_add_f32_e32 v79, v72, v79
	v_and_b32_e32 v72, 0xffff0000, v115
	v_cvt_pk_bf16_f32 v75, v80, v81
	v_add_f32_e32 v80, v73, v72
	v_lshlrev_b32_e32 v72, 16, v116
	v_add_f32_e32 v81, v66, v72
	v_and_b32_e32 v66, 0xffff0000, v116
	v_cvt_pk_bf16_f32 v76, v82, v83
	v_add_f32_e32 v82, v67, v66
	v_lshlrev_b32_e32 v66, 16, v117
	v_add_f32_e32 v83, v68, v66
	v_and_b32_e32 v66, 0xffff0000, v117
	v_cvt_pk_bf16_f32 v77, v84, v85
	v_add_f32_e32 v84, v69, v66
	v_mul_f32_e32 v66, v71, v71
	v_mul_f32_e32 v67, v80, v80
	v_fmac_f32_e32 v66, v70, v70
	v_fmac_f32_e32 v67, v79, v79
	v_add_f32_e32 v66, v66, v67
	v_mul_f32_e32 v67, v82, v82
	v_fmac_f32_e32 v67, v81, v81
	v_add_f32_e32 v66, v67, v66
	v_mul_f32_e32 v67, v84, v84
	v_fmac_f32_e32 v67, v83, v83
	v_add_f32_e32 v66, v67, v66
	v_add_f32_e32 v69, v78, v66
	ds_bpermute_b32 v78, v140, v69
	v_lshl_add_u64 v[66:67], s[4:5], 0, v[180:181]
	v_lshl_add_u64 v[72:73], v[174:175], 1, v[66:67]
	global_store_dwordx4 v[72:73], v[74:77], off nt
	v_cvt_pk_bf16_f32 v68, v70, v71
	s_waitcnt lgkmcnt(0)
	v_add_f32_e32 v66, v69, v78
	ds_bpermute_b32 v67, v141, v66
	v_cvt_pk_bf16_f32 v69, v79, v80
	v_cvt_pk_bf16_f32 v70, v81, v82
	v_cvt_pk_bf16_f32 v71, v83, v84
	global_store_dwordx4 v[72:73], v[68:71], off offset:256 nt
	s_and_saveexec_b64 s[0:1], s[40:41]
	s_cbranch_execz .LBB0_673
	s_waitcnt lgkmcnt(0)
	v_add_f32_e32 v66, v66, v67
	v_mul_f32_e32 v66, 0x4b800000, v66
	v_rndne_f32_e32 v66, v66
	v_mul_f32_e32 v67, 0x2f800000, v66
	v_floor_f32_e32 v67, v67
	v_fmac_f32_e32 v66, 0xcf800000, v67
	v_cvt_u32_f32_e32 v66, v66
	v_cvt_u32_f32_e32 v67, v67
	global_atomic_add_x2 v[138:139], v[66:67], off offset:384
.LBB0_673:
	s_or_b64 exec, exec, s[0:1]
	v_lshl_add_u64 v[104:105], v[178:179], 0, s[46:47]
	s_waitcnt lgkmcnt(0)
	v_lshl_add_u64 v[66:67], v[176:177], 0, v[104:105]
	global_load_dwordx4 v[100:103], v[66:67], off
	global_load_dwordx4 v[90:93], v[66:67], off offset:256
	s_mov_b64 s[0:1], 0x48000
	v_lshl_add_u64 v[98:99], v[178:179], 0, s[0:1]
	s_mov_b64 s[0:1], 0x50000
	v_lshl_add_u64 v[66:67], v[176:177], 0, v[98:99]
	v_lshl_add_u64 v[96:97], v[178:179], 0, s[0:1]
	s_mov_b64 s[0:1], 0x58000
	global_load_dwordx4 v[86:89], v[66:67], off
	global_load_dwordx4 v[82:85], v[66:67], off offset:256
	v_lshl_add_u64 v[66:67], v[176:177], 0, v[96:97]
	v_lshl_add_u64 v[94:95], v[178:179], 0, s[0:1]
	global_load_dwordx4 v[78:81], v[66:67], off
	global_load_dwordx4 v[74:77], v[66:67], off offset:256
	v_lshl_add_u64 v[66:67], v[176:177], 0, v[94:95]
	global_load_dwordx4 v[70:73], v[66:67], off
	s_nop 0
	global_load_dwordx4 v[66:69], v[66:67], off offset:256
	s_waitcnt vmcnt(7)
	v_lshlrev_b32_e32 v106, 16, v100
	v_add_f32_e32 v106, v62, v106
	v_and_b32_e32 v62, 0xffff0000, v100
	v_add_f32_e32 v100, v63, v62
	v_lshlrev_b32_e32 v62, 16, v101
	v_add_f32_e32 v64, v64, v62
	v_and_b32_e32 v62, 0xffff0000, v101
	v_add_f32_e32 v65, v65, v62
	v_lshlrev_b32_e32 v62, 16, v102
	v_add_f32_e32 v101, v58, v62
	v_and_b32_e32 v58, 0xffff0000, v102
	v_add_f32_e32 v102, v59, v58
	v_lshlrev_b32_e32 v58, 16, v103
	v_add_f32_e32 v107, v60, v58
	v_and_b32_e32 v58, 0xffff0000, v103
	v_lshl_add_u64 v[62:63], s[4:5], 0, v[104:105]
	v_add_f32_e32 v103, v61, v58
	v_cvt_pk_bf16_f32 v58, v106, v100
	v_cvt_pk_bf16_f32 v59, v64, v65
	v_lshl_add_u64 v[62:63], v[174:175], 1, v[62:63]
	v_cvt_pk_bf16_f32 v60, v101, v102
	v_cvt_pk_bf16_f32 v61, v107, v103
	global_store_dwordx4 v[62:63], v[58:61], off nt
	s_nop 1
	v_mul_f32_e32 v58, v100, v100
	v_mul_f32_e32 v59, v65, v65
	v_fmac_f32_e32 v58, v106, v106
	v_fmac_f32_e32 v59, v64, v64
	v_add_f32_e32 v58, v58, v59
	v_mul_f32_e32 v59, v102, v102
	v_fmac_f32_e32 v59, v101, v101
	v_add_f32_e32 v58, v59, v58
	v_mul_f32_e32 v59, v103, v103
	v_fmac_f32_e32 v59, v107, v107
	v_add_f32_e32 v58, v59, v58
	s_waitcnt vmcnt(7)
	v_lshlrev_b32_e32 v59, 16, v90
	v_add_f32_e32 v54, v54, v59
	v_and_b32_e32 v59, 0xffff0000, v90
	v_add_f32_e32 v55, v55, v59
	v_lshlrev_b32_e32 v59, 16, v91
	v_add_f32_e32 v56, v56, v59
	v_and_b32_e32 v59, 0xffff0000, v91
	v_add_f32_e32 v57, v57, v59
	v_lshlrev_b32_e32 v59, 16, v92
	v_add_f32_e32 v59, v50, v59
	v_and_b32_e32 v50, 0xffff0000, v92
	v_add_f32_e32 v60, v51, v50
	v_lshlrev_b32_e32 v50, 16, v93
	v_add_f32_e32 v61, v52, v50
	v_and_b32_e32 v50, 0xffff0000, v93
	v_add_f32_e32 v64, v53, v50
	v_cvt_pk_bf16_f32 v50, v54, v55
	v_cvt_pk_bf16_f32 v51, v56, v57
	v_cvt_pk_bf16_f32 v52, v59, v60
	v_cvt_pk_bf16_f32 v53, v61, v64
	global_store_dwordx4 v[62:63], v[50:53], off offset:256 nt
	s_nop 1
	v_mul_f32_e32 v50, v55, v55
	v_mul_f32_e32 v51, v57, v57
	v_fmac_f32_e32 v50, v54, v54
	v_fmac_f32_e32 v51, v56, v56
	v_add_f32_e32 v50, v50, v51
	v_mul_f32_e32 v51, v60, v60
	v_fmac_f32_e32 v51, v59, v59
	v_add_f32_e32 v50, v51, v50
	v_mul_f32_e32 v51, v64, v64
	v_fmac_f32_e32 v51, v61, v61
	v_add_f32_e32 v50, v51, v50
	v_add_f32_e32 v50, v58, v50
	ds_bpermute_b32 v51, v140, v50
	s_waitcnt lgkmcnt(0)
	v_add_f32_e32 v50, v50, v51
	ds_bpermute_b32 v51, v141, v50
	s_and_saveexec_b64 s[0:1], s[40:41]
	s_cbranch_execz .LBB0_675
	s_waitcnt lgkmcnt(0)
	v_add_f32_e32 v50, v50, v51
	v_mul_f32_e32 v50, 0x4b800000, v50
	v_rndne_f32_e32 v50, v50
	v_mul_f32_e32 v51, 0x2f800000, v50
	v_floor_f32_e32 v51, v51
	v_fmac_f32_e32 v50, 0xcf800000, v51
	v_cvt_u32_f32_e32 v50, v50
	v_cvt_u32_f32_e32 v51, v51
	global_atomic_add_x2 v[138:139], v[50:51], off offset:1024
.LBB0_675:
	s_or_b64 exec, exec, s[0:1]
	s_waitcnt vmcnt(7)
	v_lshlrev_b32_e32 v50, 16, v86
	v_add_f32_e32 v46, v46, v50
	v_and_b32_e32 v50, 0xffff0000, v86
	v_add_f32_e32 v47, v47, v50
	v_lshlrev_b32_e32 v50, 16, v87
	v_add_f32_e32 v48, v48, v50
	v_and_b32_e32 v50, 0xffff0000, v87
	v_add_f32_e32 v49, v49, v50
	v_lshlrev_b32_e32 v50, 16, v88
	v_add_f32_e32 v50, v42, v50
	v_and_b32_e32 v42, 0xffff0000, v88
	s_waitcnt lgkmcnt(0)
	v_add_f32_e32 v51, v43, v42
	v_lshlrev_b32_e32 v42, 16, v89
	v_add_f32_e32 v52, v44, v42
	v_and_b32_e32 v42, 0xffff0000, v89
	v_add_f32_e32 v53, v45, v42
	v_cvt_pk_bf16_f32 v42, v46, v47
	v_mul_f32_e32 v47, v47, v47
	v_fmac_f32_e32 v47, v46, v46
	v_mul_f32_e32 v46, v49, v49
	v_fmac_f32_e32 v46, v48, v48
	v_add_f32_e32 v46, v47, v46
	v_mul_f32_e32 v47, v51, v51
	v_fmac_f32_e32 v47, v50, v50
	v_add_f32_e32 v46, v47, v46
	v_mul_f32_e32 v47, v53, v53
	v_fmac_f32_e32 v47, v52, v52
	v_add_f32_e32 v46, v47, v46
	s_waitcnt vmcnt(6)
	v_lshlrev_b32_e32 v47, 16, v82
	v_add_f32_e32 v38, v38, v47
	v_and_b32_e32 v47, 0xffff0000, v82
	v_add_f32_e32 v39, v39, v47
	v_lshlrev_b32_e32 v47, 16, v83
	v_add_f32_e32 v47, v40, v47
	v_and_b32_e32 v40, 0xffff0000, v83
	v_cvt_pk_bf16_f32 v43, v48, v49
	v_add_f32_e32 v48, v41, v40
	v_lshlrev_b32_e32 v40, 16, v84
	v_add_f32_e32 v49, v34, v40
	v_and_b32_e32 v34, 0xffff0000, v84
	v_cvt_pk_bf16_f32 v44, v50, v51
	v_add_f32_e32 v50, v35, v34
	v_lshlrev_b32_e32 v34, 16, v85
	v_add_f32_e32 v51, v36, v34
	v_and_b32_e32 v34, 0xffff0000, v85
	v_cvt_pk_bf16_f32 v45, v52, v53
	v_add_f32_e32 v52, v37, v34
	v_mul_f32_e32 v34, v39, v39
	v_mul_f32_e32 v35, v48, v48
	v_fmac_f32_e32 v34, v38, v38
	v_fmac_f32_e32 v35, v47, v47
	v_add_f32_e32 v34, v34, v35
	v_mul_f32_e32 v35, v50, v50
	v_fmac_f32_e32 v35, v49, v49
	v_add_f32_e32 v34, v35, v34
	v_mul_f32_e32 v35, v52, v52
	v_fmac_f32_e32 v35, v51, v51
	v_add_f32_e32 v34, v35, v34
	v_add_f32_e32 v37, v46, v34
	ds_bpermute_b32 v46, v140, v37
	v_lshl_add_u64 v[34:35], s[4:5], 0, v[98:99]
	v_lshl_add_u64 v[40:41], v[174:175], 1, v[34:35]
	global_store_dwordx4 v[40:41], v[42:45], off nt
	v_cvt_pk_bf16_f32 v36, v38, v39
	s_waitcnt lgkmcnt(0)
	v_add_f32_e32 v34, v37, v46
	ds_bpermute_b32 v35, v141, v34
	v_cvt_pk_bf16_f32 v37, v47, v48
	v_cvt_pk_bf16_f32 v38, v49, v50
	v_cvt_pk_bf16_f32 v39, v51, v52
	global_store_dwordx4 v[40:41], v[36:39], off offset:256 nt
	s_and_saveexec_b64 s[0:1], s[40:41]
	s_cbranch_execz .LBB0_677
	s_waitcnt lgkmcnt(0)
	v_add_f32_e32 v34, v34, v35
	v_mul_f32_e32 v34, 0x4b800000, v34
	v_rndne_f32_e32 v34, v34
	v_mul_f32_e32 v35, 0x2f800000, v34
	v_floor_f32_e32 v35, v35
	v_fmac_f32_e32 v34, 0xcf800000, v35
	v_cvt_u32_f32_e32 v34, v34
	v_cvt_u32_f32_e32 v35, v35
	global_atomic_add_x2 v[138:139], v[34:35], off offset:1152
.LBB0_677:
	s_or_b64 exec, exec, s[0:1]
	s_waitcnt vmcnt(7)
	v_lshlrev_b32_e32 v34, 16, v78
	v_add_f32_e32 v30, v30, v34
	v_and_b32_e32 v34, 0xffff0000, v78
	v_add_f32_e32 v31, v31, v34
	v_lshlrev_b32_e32 v34, 16, v79
	v_add_f32_e32 v32, v32, v34
	v_and_b32_e32 v34, 0xffff0000, v79
	v_add_f32_e32 v33, v33, v34
	v_lshlrev_b32_e32 v34, 16, v80
	v_add_f32_e32 v34, v26, v34
	v_and_b32_e32 v26, 0xffff0000, v80
	s_waitcnt lgkmcnt(0)
	v_add_f32_e32 v35, v27, v26
	v_lshlrev_b32_e32 v26, 16, v81
	v_add_f32_e32 v36, v28, v26
	v_and_b32_e32 v26, 0xffff0000, v81
	v_add_f32_e32 v37, v29, v26
	v_cvt_pk_bf16_f32 v26, v30, v31
	v_mul_f32_e32 v31, v31, v31
	v_fmac_f32_e32 v31, v30, v30
	v_mul_f32_e32 v30, v33, v33
	v_fmac_f32_e32 v30, v32, v32
	v_add_f32_e32 v30, v31, v30
	v_mul_f32_e32 v31, v35, v35
	v_fmac_f32_e32 v31, v34, v34
	v_add_f32_e32 v30, v31, v30
	v_mul_f32_e32 v31, v37, v37
	v_fmac_f32_e32 v31, v36, v36
	v_add_f32_e32 v30, v31, v30
	s_waitcnt vmcnt(6)
	v_lshlrev_b32_e32 v31, 16, v74
	v_add_f32_e32 v22, v22, v31
	v_and_b32_e32 v31, 0xffff0000, v74
	v_add_f32_e32 v23, v23, v31
	v_lshlrev_b32_e32 v31, 16, v75
	v_add_f32_e32 v31, v24, v31
	v_and_b32_e32 v24, 0xffff0000, v75
	v_cvt_pk_bf16_f32 v27, v32, v33
	v_add_f32_e32 v32, v25, v24
	v_lshlrev_b32_e32 v24, 16, v76
	v_add_f32_e32 v33, v18, v24
	v_and_b32_e32 v18, 0xffff0000, v76
	v_cvt_pk_bf16_f32 v28, v34, v35
	v_add_f32_e32 v34, v19, v18
	v_lshlrev_b32_e32 v18, 16, v77
	v_add_f32_e32 v35, v20, v18
	v_and_b32_e32 v18, 0xffff0000, v77
	v_cvt_pk_bf16_f32 v29, v36, v37
	v_add_f32_e32 v36, v21, v18
	v_mul_f32_e32 v18, v23, v23
	v_mul_f32_e32 v19, v32, v32
	v_fmac_f32_e32 v18, v22, v22
	v_fmac_f32_e32 v19, v31, v31
	v_add_f32_e32 v18, v18, v19
	v_mul_f32_e32 v19, v34, v34
	v_fmac_f32_e32 v19, v33, v33
	v_add_f32_e32 v18, v19, v18
	v_mul_f32_e32 v19, v36, v36
	v_fmac_f32_e32 v19, v35, v35
	v_add_f32_e32 v18, v19, v18
	v_add_f32_e32 v21, v30, v18
	ds_bpermute_b32 v30, v140, v21
	v_lshl_add_u64 v[18:19], s[4:5], 0, v[96:97]
	v_lshl_add_u64 v[24:25], v[174:175], 1, v[18:19]
	global_store_dwordx4 v[24:25], v[26:29], off nt
	v_cvt_pk_bf16_f32 v20, v22, v23
	s_waitcnt lgkmcnt(0)
	v_add_f32_e32 v18, v21, v30
	ds_bpermute_b32 v19, v141, v18
	v_cvt_pk_bf16_f32 v21, v31, v32
	v_cvt_pk_bf16_f32 v22, v33, v34
	v_cvt_pk_bf16_f32 v23, v35, v36
	global_store_dwordx4 v[24:25], v[20:23], off offset:256 nt
	s_and_saveexec_b64 s[0:1], s[40:41]
	s_cbranch_execz .LBB0_679
	s_waitcnt lgkmcnt(0)
	v_add_f32_e32 v18, v18, v19
	v_mul_f32_e32 v18, 0x4b800000, v18
	v_rndne_f32_e32 v18, v18
	v_mul_f32_e32 v19, 0x2f800000, v18
	v_floor_f32_e32 v19, v19
	v_fmac_f32_e32 v18, 0xcf800000, v19
	v_cvt_u32_f32_e32 v18, v18
	v_cvt_u32_f32_e32 v19, v19
	global_atomic_add_x2 v[138:139], v[18:19], off offset:1280
.LBB0_679:
	s_or_b64 exec, exec, s[0:1]
	s_waitcnt vmcnt(7)
	v_lshlrev_b32_e32 v18, 16, v70
	v_add_f32_e32 v14, v14, v18
	v_and_b32_e32 v18, 0xffff0000, v70
	v_add_f32_e32 v15, v15, v18
	v_lshlrev_b32_e32 v18, 16, v71
	v_add_f32_e32 v16, v16, v18
	v_and_b32_e32 v18, 0xffff0000, v71
	v_add_f32_e32 v17, v17, v18
	v_lshlrev_b32_e32 v18, 16, v72
	v_add_f32_e32 v18, v10, v18
	v_and_b32_e32 v10, 0xffff0000, v72
	s_waitcnt lgkmcnt(0)
	v_add_f32_e32 v19, v11, v10
	v_lshlrev_b32_e32 v10, 16, v73
	v_add_f32_e32 v20, v12, v10
	v_and_b32_e32 v10, 0xffff0000, v73
	v_add_f32_e32 v21, v13, v10
	v_cvt_pk_bf16_f32 v10, v14, v15
	v_mul_f32_e32 v15, v15, v15
	v_fmac_f32_e32 v15, v14, v14
	v_mul_f32_e32 v14, v17, v17
	v_fmac_f32_e32 v14, v16, v16
	v_add_f32_e32 v14, v15, v14
	v_mul_f32_e32 v15, v19, v19
	v_fmac_f32_e32 v15, v18, v18
	v_add_f32_e32 v14, v15, v14
	v_mul_f32_e32 v15, v21, v21
	v_fmac_f32_e32 v15, v20, v20
	v_add_f32_e32 v14, v15, v14
	s_waitcnt vmcnt(6)
	v_lshlrev_b32_e32 v15, 16, v66
	v_add_f32_e32 v6, v6, v15
	v_and_b32_e32 v15, 0xffff0000, v66
	v_add_f32_e32 v7, v7, v15
	v_lshlrev_b32_e32 v15, 16, v67
	v_add_f32_e32 v15, v8, v15
	v_and_b32_e32 v8, 0xffff0000, v67
	v_cvt_pk_bf16_f32 v11, v16, v17
	v_add_f32_e32 v16, v9, v8
	v_lshlrev_b32_e32 v8, 16, v68
	v_add_f32_e32 v17, v2, v8
	v_and_b32_e32 v2, 0xffff0000, v68
	v_cvt_pk_bf16_f32 v12, v18, v19
	v_add_f32_e32 v18, v3, v2
	v_lshlrev_b32_e32 v2, 16, v69
	v_add_f32_e32 v19, v4, v2
	v_and_b32_e32 v2, 0xffff0000, v69
	v_cvt_pk_bf16_f32 v13, v20, v21
	v_add_f32_e32 v20, v5, v2
	v_mul_f32_e32 v2, v7, v7
	v_mul_f32_e32 v3, v16, v16
	v_fmac_f32_e32 v2, v6, v6
	v_fmac_f32_e32 v3, v15, v15
	v_add_f32_e32 v2, v2, v3
	v_mul_f32_e32 v3, v18, v18
	v_fmac_f32_e32 v3, v17, v17
	v_add_f32_e32 v2, v3, v2
	v_mul_f32_e32 v3, v20, v20
	v_fmac_f32_e32 v3, v19, v19
	v_add_f32_e32 v2, v3, v2
	v_add_f32_e32 v5, v14, v2
	ds_bpermute_b32 v14, v140, v5
	v_lshl_add_u64 v[2:3], s[4:5], 0, v[94:95]
	v_lshl_add_u64 v[8:9], v[174:175], 1, v[2:3]
	global_store_dwordx4 v[8:9], v[10:13], off nt
	v_cvt_pk_bf16_f32 v4, v6, v7
	s_waitcnt lgkmcnt(0)
	v_add_f32_e32 v2, v5, v14
	ds_bpermute_b32 v3, v141, v2
	v_cvt_pk_bf16_f32 v5, v15, v16
	v_cvt_pk_bf16_f32 v6, v17, v18
	v_cvt_pk_bf16_f32 v7, v19, v20
	global_store_dwordx4 v[8:9], v[4:7], off offset:256 nt
	s_and_saveexec_b64 s[0:1], s[40:41]
	s_cbranch_execz .LBB0_681
	s_waitcnt lgkmcnt(0)
	v_add_f32_e32 v2, v2, v3
	v_mul_f32_e32 v2, 0x4b800000, v2
	v_rndne_f32_e32 v2, v2
	v_mul_f32_e32 v3, 0x2f800000, v2
	v_floor_f32_e32 v3, v3
	v_fmac_f32_e32 v2, 0xcf800000, v3
	v_cvt_u32_f32_e32 v2, v2
	v_cvt_u32_f32_e32 v3, v3
	global_atomic_add_x2 v[138:139], v[2:3], off offset:1408

.LBB0_703:
	v_mov_b32_e32 v122, s28
	v_mov_b32_e32 v123, s25
	v_lshl_add_u64 v[122:123], v[140:141], 1, v[122:123]
	v_mad_i64_i32 v[172:173], s[28:29], s24, v142, 0
	s_andn2_b64 vcc, exec, s[6:7]
	v_lshl_add_u64 v[172:173], v[172:173], 1, v[122:123]
	s_cbranch_vccnz .LBB0_705
	v_cvt_pk_bf16_f32 v178, v170, v171
	v_cvt_pk_bf16_f32 v179, v128, v129
	v_cvt_pk_bf16_f32 v180, v126, v127
	v_cvt_pk_bf16_f32 v181, v124, v125
	global_store_dwordx4 v[172:173], v[178:181], off nt

.LBB0_707:
	s_andn2_b64 vcc, exec, s[0:1]
	s_cbranch_vccnz .LBB0_709
	v_cvt_pk_bf16_f32 v118, v118, v119
	v_cvt_pk_bf16_f32 v119, v120, v121
	v_cvt_pk_bf16_f32 v120, v114, v115
	v_cvt_pk_bf16_f32 v121, v116, v117
	global_store_dwordx4 v[172:173], v[118:121], off offset:256 nt

.LBB0_711:
	v_mad_i64_i32 v[106:107], s[6:7], s24, v118, 0
	s_andn2_b64 vcc, exec, s[0:1]
	v_lshl_add_u64 v[106:107], v[106:107], 1, v[122:123]
	s_cbranch_vccnz .LBB0_713
	v_cvt_pk_bf16_f32 v124, v116, v117
	v_cvt_pk_bf16_f32 v125, v112, v113
	v_cvt_pk_bf16_f32 v126, v110, v111
	v_cvt_pk_bf16_f32 v127, v108, v109
	global_store_dwordx4 v[106:107], v[124:127], off nt

.LBB0_715:
	s_andn2_b64 vcc, exec, s[0:1]
	s_cbranch_vccnz .LBB0_717
	v_cvt_pk_bf16_f32 v102, v102, v103
	v_cvt_pk_bf16_f32 v103, v104, v105
	v_cvt_pk_bf16_f32 v104, v98, v99
	v_cvt_pk_bf16_f32 v105, v100, v101
	global_store_dwordx4 v[106:107], v[102:105], off offset:256 nt

.LBB0_719:
	v_mad_i64_i32 v[90:91], s[6:7], s24, v102, 0
	s_andn2_b64 vcc, exec, s[0:1]
	v_lshl_add_u64 v[90:91], v[90:91], 1, v[122:123]
	s_cbranch_vccnz .LBB0_721
	v_cvt_pk_bf16_f32 v104, v100, v101
	v_cvt_pk_bf16_f32 v105, v96, v97
	v_cvt_pk_bf16_f32 v106, v94, v95
	v_cvt_pk_bf16_f32 v107, v92, v93
	global_store_dwordx4 v[90:91], v[104:107], off nt

.LBB0_723:
	s_andn2_b64 vcc, exec, s[0:1]
	s_cbranch_vccnz .LBB0_725
	v_cvt_pk_bf16_f32 v86, v86, v87
	v_cvt_pk_bf16_f32 v87, v88, v89
	v_cvt_pk_bf16_f32 v88, v82, v83
	v_cvt_pk_bf16_f32 v89, v84, v85
	global_store_dwordx4 v[90:91], v[86:89], off offset:256 nt

.LBB0_727:
	v_mad_i64_i32 v[74:75], s[6:7], s24, v86, 0
	s_andn2_b64 vcc, exec, s[0:1]
	v_lshl_add_u64 v[74:75], v[74:75], 1, v[122:123]
	s_cbranch_vccnz .LBB0_729
	v_cvt_pk_bf16_f32 v88, v84, v85
	v_cvt_pk_bf16_f32 v89, v80, v81
	v_cvt_pk_bf16_f32 v90, v78, v79
	v_cvt_pk_bf16_f32 v91, v76, v77
	global_store_dwordx4 v[74:75], v[88:91], off nt

.LBB0_731:
	s_andn2_b64 vcc, exec, s[0:1]
	s_cbranch_vccnz .LBB0_733
	v_cvt_pk_bf16_f32 v70, v70, v71
	v_cvt_pk_bf16_f32 v71, v72, v73
	v_cvt_pk_bf16_f32 v72, v66, v67
	v_cvt_pk_bf16_f32 v73, v68, v69
	global_store_dwordx4 v[74:75], v[70:73], off offset:256 nt

.LBB0_735:
	v_mad_i64_i32 v[58:59], s[6:7], s24, v70, 0
	s_andn2_b64 vcc, exec, s[0:1]
	v_lshl_add_u64 v[58:59], v[58:59], 1, v[122:123]
	s_cbranch_vccnz .LBB0_737
	v_cvt_pk_bf16_f32 v72, v68, v69
	v_cvt_pk_bf16_f32 v73, v64, v65
	v_cvt_pk_bf16_f32 v74, v62, v63
	v_cvt_pk_bf16_f32 v75, v60, v61
	global_store_dwordx4 v[58:59], v[72:75], off nt

.LBB0_739:
	s_andn2_b64 vcc, exec, s[0:1]
	s_cbranch_vccnz .LBB0_741
	v_cvt_pk_bf16_f32 v54, v54, v55
	v_cvt_pk_bf16_f32 v55, v56, v57
	v_cvt_pk_bf16_f32 v56, v50, v51
	v_cvt_pk_bf16_f32 v57, v52, v53
	global_store_dwordx4 v[58:59], v[54:57], off offset:256 nt

.LBB0_743:
	v_mad_i64_i32 v[42:43], s[6:7], s24, v54, 0
	s_andn2_b64 vcc, exec, s[0:1]
	v_lshl_add_u64 v[42:43], v[42:43], 1, v[122:123]
	s_cbranch_vccnz .LBB0_745
	v_cvt_pk_bf16_f32 v56, v52, v53
	v_cvt_pk_bf16_f32 v57, v48, v49
	v_cvt_pk_bf16_f32 v58, v46, v47
	v_cvt_pk_bf16_f32 v59, v44, v45
	global_store_dwordx4 v[42:43], v[56:59], off nt

.LBB0_747:
	s_andn2_b64 vcc, exec, s[0:1]
	s_cbranch_vccnz .LBB0_749
	v_cvt_pk_bf16_f32 v38, v38, v39
	v_cvt_pk_bf16_f32 v39, v40, v41
	v_cvt_pk_bf16_f32 v40, v34, v35
	v_cvt_pk_bf16_f32 v41, v36, v37
	global_store_dwordx4 v[42:43], v[38:41], off offset:256 nt

.LBB0_751:
	v_mad_i64_i32 v[26:27], s[6:7], s24, v38, 0
	s_andn2_b64 vcc, exec, s[0:1]
	v_lshl_add_u64 v[26:27], v[26:27], 1, v[122:123]
	s_cbranch_vccnz .LBB0_753
	v_cvt_pk_bf16_f32 v40, v36, v37
	v_cvt_pk_bf16_f32 v41, v32, v33
	v_cvt_pk_bf16_f32 v42, v30, v31
	v_cvt_pk_bf16_f32 v43, v28, v29
	global_store_dwordx4 v[26:27], v[40:43], off nt

.LBB0_755:
	s_andn2_b64 vcc, exec, s[0:1]
	s_cbranch_vccnz .LBB0_757
	v_cvt_pk_bf16_f32 v22, v22, v23
	v_cvt_pk_bf16_f32 v23, v24, v25
	v_cvt_pk_bf16_f32 v24, v18, v19
	v_cvt_pk_bf16_f32 v25, v20, v21
	global_store_dwordx4 v[26:27], v[22:25], off offset:256 nt

.LBB0_759:
	v_mad_i64_i32 v[10:11], s[6:7], s24, v22, 0
	s_andn2_b64 vcc, exec, s[0:1]
	v_lshl_add_u64 v[10:11], v[10:11], 1, v[122:123]
	s_cbranch_vccnz .LBB0_761
	v_cvt_pk_bf16_f32 v24, v20, v21
	v_cvt_pk_bf16_f32 v25, v16, v17
	v_cvt_pk_bf16_f32 v26, v14, v15
	v_cvt_pk_bf16_f32 v27, v12, v13
	global_store_dwordx4 v[10:11], v[24:27], off nt

.LBB0_765:
	v_cvt_pk_bf16_f32 v6, v6, v7
	v_cvt_pk_bf16_f32 v7, v8, v9
	v_cvt_pk_bf16_f32 v8, v2, v3
	v_cvt_pk_bf16_f32 v9, v4, v5
	global_store_dwordx4 v[10:11], v[6:9], off offset:256 nt
	s_andn2_b64 vcc, exec, s[40:41]
	s_mov_b64 s[0:1], -1
	s_cbranch_vccnz .LBB0_694

.LBB0_781:
	v_lshl_or_b32 v174, s22, 8, v180
	v_ashrrev_i32_e32 v175, 31, v174
	v_lshl_add_u64 v[142:143], v[174:175], 3, s[2:3]
	global_load_dwordx4 v[130:133], v[142:143], off offset:48
	global_load_dwordx4 v[134:137], v[142:143], off offset:32
	global_load_dwordx4 v[138:141], v[142:143], off offset:16
	global_load_dwordx4 v[156:159], v[142:143], off
	s_mov_b32 s6, 0x33800000
	s_mov_b32 s0, 0x358637bd
	v_mov_b64_e32 v[176:177], s[0:1]
	s_mov_b32 s22, 0x3a800000
	s_mov_b32 s0, 0x800000
	s_mov_b32 s24, 0x45800000
	s_waitcnt vmcnt(0)
	v_ffbh_u32_e32 v144, v159
	v_min_u32_e32 v170, 32, v144
	v_lshlrev_b64 v[144:145], v170, v[158:159]
	v_min_u32_e32 v144, 1, v144
	v_or_b32_e32 v144, v145, v144
	v_cvt_f32_u32_e32 v144, v144
	v_sub_u32_e32 v145, 32, v170
	v_ldexp_f32 v145, v144, v145
	v_ffbh_u32_e32 v144, v157
	v_min_u32_e32 v144, 32, v144
	v_lshlrev_b64 v[156:157], v144, v[156:157]
	v_min_u32_e32 v156, 1, v156
	v_or_b32_e32 v156, v157, v156
	v_cvt_f32_u32_e32 v156, v156
	v_sub_u32_e32 v144, 32, v144
	v_ldexp_f32 v144, v156, v144
	v_pk_mul_f32 v[144:145], v[144:145], s[6:7] op_sel_hi:[1,0]
	s_nop 0
	v_pk_fma_f32 v[144:145], v[144:145], s[22:23], v[176:177] op_sel_hi:[1,0,0]
	s_nop 0
	v_mul_f32_e32 v156, 0x4b800000, v144
	v_cmp_gt_f32_e64 s[42:43], s0, v144
	v_cmp_gt_f32_e32 vcc, s0, v145
	s_nop 0
	v_cndmask_b32_e64 v144, v144, v156, s[42:43]
	v_mul_f32_e32 v156, 0x4b800000, v145
	v_cndmask_b32_e32 v145, v145, v156, vcc
	v_rsq_f32_e32 v144, v144
	v_rsq_f32_e32 v145, v145
	s_nop 0
	v_pk_mul_f32 v[156:157], v[144:145], s[24:25] op_sel_hi:[1,0]
	s_nop 0
	v_cndmask_b32_e64 v156, v144, v156, s[42:43]
	v_ffbh_u32_e32 v144, v141
	v_min_u32_e32 v144, 32, v144
	v_lshlrev_b64 v[140:141], v144, v[140:141]
	v_min_u32_e32 v140, 1, v140
	v_or_b32_e32 v140, v141, v140
	v_cvt_f32_u32_e32 v140, v140
	v_sub_u32_e32 v141, 32, v144
	v_cndmask_b32_e32 v157, v145, v157, vcc
	v_pk_mul_f32 v[126:127], v[126:127], v[156:157]
	v_ldexp_f32 v141, v140, v141
	v_ffbh_u32_e32 v140, v139
	v_min_u32_e32 v140, 32, v140
	v_lshlrev_b64 v[138:139], v140, v[138:139]
	v_min_u32_e32 v138, 1, v138
	v_or_b32_e32 v138, v139, v138
	v_cvt_f32_u32_e32 v138, v138
	v_sub_u32_e32 v139, 32, v140
	v_pk_mul_f32 v[114:115], v[114:115], v[156:157]
	v_pk_mul_f32 v[98:99], v[98:99], v[156:157]
	v_ldexp_f32 v140, v138, v139
	v_pk_mul_f32 v[138:139], v[140:141], s[6:7] op_sel_hi:[1,0]
	v_pk_mul_f32 v[82:83], v[82:83], v[156:157]
	v_pk_fma_f32 v[138:139], v[138:139], s[22:23], v[176:177] op_sel_hi:[1,0,0]
	v_pk_mul_f32 v[62:63], v[62:63], v[156:157]
	v_mul_f32_e32 v140, 0x4b800000, v138
	v_cmp_gt_f32_e64 s[42:43], s0, v138
	v_cmp_gt_f32_e32 vcc, s0, v139
	v_pk_mul_f32 v[50:51], v[50:51], v[156:157]
	v_cndmask_b32_e64 v138, v138, v140, s[42:43]
	v_mul_f32_e32 v140, 0x4b800000, v139
	v_cndmask_b32_e32 v139, v139, v140, vcc
	v_rsq_f32_e32 v138, v138
	v_rsq_f32_e32 v139, v139
	v_pk_mul_f32 v[34:35], v[34:35], v[156:157]
	v_pk_mul_f32 v[18:19], v[18:19], v[156:157]
	v_pk_mul_f32 v[140:141], v[138:139], s[24:25] op_sel_hi:[1,0]
	s_nop 0
	v_cndmask_b32_e64 v158, v138, v140, s[42:43]
	v_ffbh_u32_e32 v138, v137
	v_min_u32_e32 v138, 32, v138
	v_lshlrev_b64 v[136:137], v138, v[136:137]
	v_min_u32_e32 v136, 1, v136
	v_or_b32_e32 v136, v137, v136
	v_cvt_f32_u32_e32 v136, v136
	v_sub_u32_e32 v137, 32, v138
	v_cndmask_b32_e32 v159, v139, v141, vcc
	v_pk_mul_f32 v[128:129], v[128:129], v[158:159]
	v_ldexp_f32 v137, v136, v137
	v_ffbh_u32_e32 v136, v135
	v_min_u32_e32 v136, 32, v136
	v_lshlrev_b64 v[134:135], v136, v[134:135]
	v_min_u32_e32 v134, 1, v134
	v_or_b32_e32 v134, v135, v134
	v_cvt_f32_u32_e32 v134, v134
	v_sub_u32_e32 v135, 32, v136
	v_pk_mul_f32 v[64:65], v[64:65], v[158:159]
	v_ldexp_f32 v136, v134, v135
	v_pk_mul_f32 v[134:135], v[136:137], s[6:7] op_sel_hi:[1,0]
	s_nop 0
	v_pk_fma_f32 v[134:135], v[134:135], s[22:23], v[176:177] op_sel_hi:[1,0,0]
	s_nop 0
	v_mul_f32_e32 v136, 0x4b800000, v134
	v_cmp_gt_f32_e64 s[42:43], s0, v134
	v_cmp_gt_f32_e32 vcc, s0, v135
	s_nop 0
	v_cndmask_b32_e64 v134, v134, v136, s[42:43]
	v_mul_f32_e32 v136, 0x4b800000, v135
	v_cndmask_b32_e32 v135, v135, v136, vcc
	v_rsq_f32_e32 v134, v134
	v_rsq_f32_e32 v135, v135
	s_nop 0
	v_pk_mul_f32 v[136:137], v[134:135], s[24:25] op_sel_hi:[1,0]
	s_nop 0
	v_cndmask_b32_e64 v170, v134, v136, s[42:43]
	v_ffbh_u32_e32 v134, v133
	v_min_u32_e32 v134, 32, v134
	v_lshlrev_b64 v[132:133], v134, v[132:133]
	v_min_u32_e32 v132, 1, v132
	v_or_b32_e32 v132, v133, v132
	v_cvt_f32_u32_e32 v132, v132
	v_sub_u32_e32 v133, 32, v134
	v_cndmask_b32_e32 v171, v135, v137, vcc
	v_ldexp_f32 v133, v132, v133
	v_ffbh_u32_e32 v132, v131
	v_min_u32_e32 v132, 32, v132
	v_lshlrev_b64 v[130:131], v132, v[130:131]
	v_min_u32_e32 v130, 1, v130
	v_or_b32_e32 v130, v131, v130
	v_cvt_f32_u32_e32 v130, v130
	v_sub_u32_e32 v131, 32, v132
	v_ldexp_f32 v132, v130, v131
	v_pk_mul_f32 v[130:131], v[132:133], s[6:7] op_sel_hi:[1,0]
	s_nop 0
	v_pk_fma_f32 v[130:131], v[130:131], s[22:23], v[176:177] op_sel_hi:[1,0,0]
	s_nop 0
	v_mul_f32_e32 v132, 0x4b800000, v130
	v_cmp_gt_f32_e64 s[42:43], s0, v130
	v_cmp_gt_f32_e32 vcc, s0, v131
	s_nop 0
	v_cndmask_b32_e64 v130, v130, v132, s[42:43]
	v_mul_f32_e32 v132, 0x4b800000, v131
	v_cndmask_b32_e32 v131, v131, v132, vcc
	v_rsq_f32_e32 v130, v130
	v_rsq_f32_e32 v131, v131
	s_nop 0
	v_pk_mul_f32 v[132:133], v[130:131], s[24:25] op_sel_hi:[1,0]
	s_nop 0
	v_cndmask_b32_e32 v173, v131, v133, vcc
	v_cndmask_b32_e64 v172, v130, v132, s[42:43]
	global_load_dwordx4 v[130:133], v[142:143], off offset:1072
	global_load_dwordx4 v[134:137], v[142:143], off offset:1056
	global_load_dwordx4 v[138:141], v[142:143], off offset:1040
	s_nop 0
	global_load_dwordx4 v[142:145], v[142:143], off offset:1024
	s_waitcnt vmcnt(0)
	v_ffbh_u32_e32 v182, v145
	v_min_u32_e32 v182, 32, v182
	v_lshlrev_b64 v[144:145], v182, v[144:145]
	v_min_u32_e32 v144, 1, v144
	v_or_b32_e32 v144, v145, v144
	v_cvt_f32_u32_e32 v144, v144
	v_sub_u32_e32 v145, 32, v182
	v_ldexp_f32 v145, v144, v145
	v_ffbh_u32_e32 v144, v143
	v_min_u32_e32 v144, 32, v144
	v_lshlrev_b64 v[142:143], v144, v[142:143]
	v_min_u32_e32 v142, 1, v142
	v_or_b32_e32 v142, v143, v142
	v_cvt_f32_u32_e32 v142, v142
	v_sub_u32_e32 v143, 32, v144
	v_ldexp_f32 v144, v142, v143
	v_pk_mul_f32 v[142:143], v[144:145], s[6:7] op_sel_hi:[1,0]
	s_nop 0
	v_pk_fma_f32 v[142:143], v[142:143], s[22:23], v[176:177] op_sel_hi:[1,0,0]
	s_nop 0
	v_mul_f32_e32 v144, 0x4b800000, v142
	v_cmp_gt_f32_e64 s[42:43], s0, v142
	v_cmp_gt_f32_e32 vcc, s0, v143
	s_nop 0
	v_cndmask_b32_e64 v142, v142, v144, s[42:43]
	v_mul_f32_e32 v144, 0x4b800000, v143
	v_cndmask_b32_e32 v143, v143, v144, vcc
	v_rsq_f32_e32 v142, v142
	v_rsq_f32_e32 v143, v143
	s_nop 0
	v_pk_mul_f32 v[144:145], v[142:143], s[24:25] op_sel_hi:[1,0]
	s_nop 0
	v_cndmask_b32_e64 v142, v142, v144, s[42:43]
	v_ffbh_u32_e32 v144, v141
	v_min_u32_e32 v144, 32, v144
	v_lshlrev_b64 v[140:141], v144, v[140:141]
	v_min_u32_e32 v140, 1, v140
	v_or_b32_e32 v140, v141, v140
	v_cvt_f32_u32_e32 v140, v140
	v_sub_u32_e32 v141, 32, v144
	v_cndmask_b32_e32 v143, v143, v145, vcc
	v_pk_mul_f32 v[144:145], v[124:125], v[172:173]
	v_ldexp_f32 v141, v140, v141
	v_ffbh_u32_e32 v140, v139
	v_min_u32_e32 v140, 32, v140
	v_lshlrev_b64 v[138:139], v140, v[138:139]
	v_min_u32_e32 v138, 1, v138
	v_or_b32_e32 v138, v139, v138
	v_cvt_f32_u32_e32 v138, v138
	v_sub_u32_e32 v139, 32, v140
	v_pk_mul_f32 v[124:125], v[122:123], v[170:171]
	v_cvt_pk_bf16_f32 v122, v126, v127
	v_ldexp_f32 v140, v138, v139
	v_pk_mul_f32 v[138:139], v[140:141], s[6:7] op_sel_hi:[1,0]
	v_cvt_pk_bf16_f32 v123, v128, v129
	v_cvt_pk_bf16_f32 v124, v124, v125
	v_cvt_pk_bf16_f32 v125, v144, v145
	v_pk_mul_f32 v[118:119], v[118:119], v[142:143]
	v_pk_fma_f32 v[138:139], v[138:139], s[22:23], v[176:177] op_sel_hi:[1,0,0]
	v_pk_mul_f32 v[102:103], v[102:103], v[142:143]
	v_mul_f32_e32 v140, 0x4b800000, v138
	v_cmp_gt_f32_e64 s[42:43], s0, v138
	v_cmp_gt_f32_e32 vcc, s0, v139
	v_pk_mul_f32 v[86:87], v[86:87], v[142:143]
	v_cndmask_b32_e64 v138, v138, v140, s[42:43]
	v_mul_f32_e32 v140, 0x4b800000, v139
	v_cndmask_b32_e32 v139, v139, v140, vcc
	v_rsq_f32_e32 v138, v138
	v_rsq_f32_e32 v139, v139
	v_pk_mul_f32 v[70:71], v[70:71], v[142:143]
	v_pk_mul_f32 v[54:55], v[54:55], v[142:143]
	v_pk_mul_f32 v[38:39], v[38:39], v[142:143]
	v_pk_mul_f32 v[140:141], v[138:139], s[24:25] op_sel_hi:[1,0]
	v_pk_mul_f32 v[22:23], v[22:23], v[142:143]
	v_cndmask_b32_e64 v138, v138, v140, s[42:43]
	v_ffbh_u32_e32 v140, v137
	v_min_u32_e32 v140, 32, v140
	v_lshlrev_b64 v[136:137], v140, v[136:137]
	v_min_u32_e32 v136, 1, v136
	v_or_b32_e32 v136, v137, v136
	v_cvt_f32_u32_e32 v136, v136
	v_sub_u32_e32 v137, 32, v140
	v_cndmask_b32_e32 v139, v139, v141, vcc
	v_lshlrev_b64 v[140:141], 1, v[174:175]
	v_ldexp_f32 v137, v136, v137
	v_ffbh_u32_e32 v136, v135
	v_min_u32_e32 v136, 32, v136
	v_lshlrev_b64 v[134:135], v136, v[134:135]
	v_min_u32_e32 v134, 1, v134
	v_or_b32_e32 v134, v135, v134
	v_cvt_f32_u32_e32 v134, v134
	v_sub_u32_e32 v135, 32, v136
	v_pk_mul_f32 v[120:121], v[120:121], v[138:139]
	v_pk_mul_f32 v[104:105], v[104:105], v[138:139]
	v_ldexp_f32 v136, v134, v135
	v_pk_mul_f32 v[134:135], v[136:137], s[6:7] op_sel_hi:[1,0]
	v_pk_mul_f32 v[88:89], v[88:89], v[138:139]
	v_pk_fma_f32 v[134:135], v[134:135], s[22:23], v[176:177] op_sel_hi:[1,0,0]
	v_pk_mul_f32 v[72:73], v[72:73], v[138:139]
	v_mul_f32_e32 v136, 0x4b800000, v134
	v_cmp_gt_f32_e64 s[42:43], s0, v134
	v_cmp_gt_f32_e32 vcc, s0, v135
	v_pk_mul_f32 v[56:57], v[56:57], v[138:139]
	v_cndmask_b32_e64 v134, v134, v136, s[42:43]
	v_mul_f32_e32 v136, 0x4b800000, v135
	v_cndmask_b32_e32 v135, v135, v136, vcc
	v_rsq_f32_e32 v134, v134
	v_rsq_f32_e32 v135, v135
	v_pk_mul_f32 v[40:41], v[40:41], v[138:139]
	v_pk_mul_f32 v[24:25], v[24:25], v[138:139]
	v_pk_mul_f32 v[8:9], v[8:9], v[138:139]
	v_pk_mul_f32 v[136:137], v[134:135], s[24:25] op_sel_hi:[1,0]
	v_pk_mul_f32 v[6:7], v[6:7], v[142:143]
	v_cndmask_b32_e64 v134, v134, v136, s[42:43]
	v_ffbh_u32_e32 v136, v133
	v_min_u32_e32 v136, 32, v136
	v_lshlrev_b64 v[132:133], v136, v[132:133]
	v_min_u32_e32 v132, 1, v132
	v_or_b32_e32 v132, v133, v132
	v_cvt_f32_u32_e32 v132, v132
	v_sub_u32_e32 v133, 32, v136
	v_cndmask_b32_e32 v135, v135, v137, vcc
	v_lshl_add_u32 v136, s54, 8, v178
	v_ldexp_f32 v133, v132, v133
	v_ffbh_u32_e32 v132, v131
	v_min_u32_e32 v132, 32, v132
	v_lshlrev_b64 v[130:131], v132, v[130:131]
	v_min_u32_e32 v130, 1, v130
	v_or_b32_e32 v130, v131, v130
	v_cvt_f32_u32_e32 v130, v130
	v_sub_u32_e32 v131, 32, v132
	v_ashrrev_i32_e32 v137, 31, v136
	v_ldexp_f32 v132, v130, v131
	v_pk_mul_f32 v[130:131], v[132:133], s[6:7] op_sel_hi:[1,0]
	s_nop 0
	v_pk_fma_f32 v[130:131], v[130:131], s[22:23], v[176:177] op_sel_hi:[1,0,0]
	s_mov_b32 s23, 0xb000
	v_mul_f32_e32 v132, 0x4b800000, v130
	v_cmp_gt_f32_e64 s[42:43], s0, v130
	v_cmp_gt_f32_e32 vcc, s0, v131
	s_mov_b64 s[0:1], 0x400000
	v_cndmask_b32_e64 v130, v130, v132, s[42:43]
	v_mul_f32_e32 v132, 0x4b800000, v131
	v_cndmask_b32_e32 v131, v131, v132, vcc
	v_rsq_f32_e32 v130, v130
	v_rsq_f32_e32 v131, v131
	s_nop 0
	v_pk_mul_f32 v[132:133], v[130:131], s[24:25] op_sel_hi:[1,0]
	s_nop 0
	v_cndmask_b32_e32 v131, v131, v133, vcc
	v_cndmask_b32_e64 v130, v130, v132, s[42:43]
	v_lshlrev_b64 v[132:133], 15, v[136:137]
	v_lshl_add_u64 v[132:133], s[30:31], 0, v[132:133]
	v_lshl_add_u64 v[132:133], v[132:133], 0, v[140:141]
	global_store_dwordx4 v[132:133], v[122:125], off nt
	s_nop 1
	v_pk_mul_f32 v[122:123], v[112:113], v[130:131]
	v_pk_mul_f32 v[112:113], v[110:111], v[134:135]
	v_cvt_pk_bf16_f32 v110, v118, v119
	v_cvt_pk_bf16_f32 v111, v120, v121
	s_nop 0
	v_cvt_pk_bf16_f32 v112, v112, v113
	v_cvt_pk_bf16_f32 v113, v122, v123
	global_store_dwordx4 v[132:133], v[110:113], off offset:256 nt
	s_nop 1
	v_or_b32_e32 v110, 16, v136
	v_ashrrev_i32_e32 v111, 31, v110
	v_lshlrev_b64 v[110:111], 15, v[110:111]
	v_lshl_add_u64 v[110:111], s[30:31], 0, v[110:111]
	v_lshl_add_u64 v[110:111], v[110:111], 0, v[140:141]
	v_pk_mul_f32 v[112:113], v[116:117], v[158:159]
	v_pk_mul_f32 v[116:117], v[108:109], v[172:173]
	v_pk_mul_f32 v[108:109], v[106:107], v[170:171]
	v_cvt_pk_bf16_f32 v106, v114, v115
	v_cvt_pk_bf16_f32 v107, v112, v113
	s_nop 0
	v_cvt_pk_bf16_f32 v108, v108, v109
	v_cvt_pk_bf16_f32 v109, v116, v117
	global_store_dwordx4 v[110:111], v[106:109], off nt
	s_nop 1
	v_pk_mul_f32 v[106:107], v[96:97], v[130:131]
	v_pk_mul_f32 v[96:97], v[94:95], v[134:135]
	v_cvt_pk_bf16_f32 v94, v102, v103
	v_cvt_pk_bf16_f32 v95, v104, v105
	s_nop 0
	v_cvt_pk_bf16_f32 v96, v96, v97
	v_cvt_pk_bf16_f32 v97, v106, v107
	global_store_dwordx4 v[110:111], v[94:97], off offset:256 nt
	s_nop 1
	v_or_b32_e32 v94, 32, v136
	v_ashrrev_i32_e32 v95, 31, v94
	v_lshlrev_b64 v[94:95], 15, v[94:95]
	v_lshl_add_u64 v[94:95], s[30:31], 0, v[94:95]
	v_lshl_add_u64 v[94:95], v[94:95], 0, v[140:141]
	v_pk_mul_f32 v[96:97], v[100:101], v[158:159]
	v_pk_mul_f32 v[100:101], v[92:93], v[172:173]
	v_pk_mul_f32 v[92:93], v[90:91], v[170:171]
	v_cvt_pk_bf16_f32 v90, v98, v99
	v_cvt_pk_bf16_f32 v91, v96, v97
	s_nop 0
	v_cvt_pk_bf16_f32 v92, v92, v93
	v_cvt_pk_bf16_f32 v93, v100, v101
	global_store_dwordx4 v[94:95], v[90:93], off nt
	s_nop 1
	v_pk_mul_f32 v[90:91], v[80:81], v[130:131]
	v_pk_mul_f32 v[80:81], v[78:79], v[134:135]
	v_cvt_pk_bf16_f32 v78, v86, v87
	v_cvt_pk_bf16_f32 v79, v88, v89
	s_nop 0
	v_cvt_pk_bf16_f32 v80, v80, v81
	v_cvt_pk_bf16_f32 v81, v90, v91
	global_store_dwordx4 v[94:95], v[78:81], off offset:256 nt
	s_nop 1
	v_or_b32_e32 v78, 48, v136
	v_ashrrev_i32_e32 v79, 31, v78
	v_lshlrev_b64 v[78:79], 15, v[78:79]
	v_lshl_add_u64 v[78:79], s[30:31], 0, v[78:79]
	v_lshl_add_u64 v[78:79], v[78:79], 0, v[140:141]
	v_pk_mul_f32 v[80:81], v[84:85], v[158:159]
	v_pk_mul_f32 v[84:85], v[76:77], v[172:173]
	v_pk_mul_f32 v[76:77], v[74:75], v[170:171]
	v_cvt_pk_bf16_f32 v74, v82, v83
	v_cvt_pk_bf16_f32 v75, v80, v81
	s_nop 0
	v_cvt_pk_bf16_f32 v76, v76, v77
	v_cvt_pk_bf16_f32 v77, v84, v85
	global_store_dwordx4 v[78:79], v[74:77], off nt
	s_nop 1
	v_pk_mul_f32 v[74:75], v[68:69], v[130:131]
	v_pk_mul_f32 v[68:69], v[66:67], v[134:135]
	v_cvt_pk_bf16_f32 v66, v70, v71
	v_cvt_pk_bf16_f32 v67, v72, v73
	s_nop 0
	v_cvt_pk_bf16_f32 v68, v68, v69
	v_cvt_pk_bf16_f32 v69, v74, v75
	global_store_dwordx4 v[78:79], v[66:69], off offset:256 nt
	s_nop 1
	v_lshl_add_u64 v[66:67], v[132:133], 0, s[0:1]
	s_mov_b32 s0, 0x400000
	v_pk_mul_f32 v[68:69], v[60:61], v[172:173]
	v_pk_mul_f32 v[60:61], v[58:59], v[170:171]
	v_cvt_pk_bf16_f32 v58, v62, v63
	v_add_co_u32_e32 v62, vcc, s0, v132
	v_cvt_pk_bf16_f32 v59, v64, v65
	v_cvt_pk_bf16_f32 v60, v60, v61
	v_cvt_pk_bf16_f32 v61, v68, v69
	s_mov_b64 s[0:1], 0x480000
	s_nop 0
	v_addc_co_u32_e32 v63, vcc, 0, v133, vcc
	global_store_dwordx4 v[62:63], v[58:61], off nt
	s_nop 1
	v_pk_mul_f32 v[58:59], v[48:49], v[130:131]
	v_pk_mul_f32 v[48:49], v[46:47], v[134:135]
	v_cvt_pk_bf16_f32 v46, v54, v55
	v_cvt_pk_bf16_f32 v47, v56, v57
	s_nop 0
	v_cvt_pk_bf16_f32 v48, v48, v49
	v_cvt_pk_bf16_f32 v49, v58, v59
	global_store_dwordx4 v[66:67], v[46:49], off offset:256 nt
	s_nop 1
	v_lshl_add_u64 v[46:47], v[132:133], 0, s[0:1]
	v_pk_mul_f32 v[48:49], v[52:53], v[158:159]
	s_mov_b32 s0, 0x480000
	v_pk_mul_f32 v[52:53], v[44:45], v[172:173]
	v_pk_mul_f32 v[44:45], v[42:43], v[170:171]
	v_cvt_pk_bf16_f32 v43, v48, v49
	v_add_co_u32_e32 v48, vcc, s0, v132
	v_cvt_pk_bf16_f32 v42, v50, v51
	v_cvt_pk_bf16_f32 v44, v44, v45
	v_cvt_pk_bf16_f32 v45, v52, v53
	s_mov_b64 s[0:1], 0x500000
	s_nop 0
	v_addc_co_u32_e32 v49, vcc, 0, v133, vcc
	global_store_dwordx4 v[48:49], v[42:45], off nt
	s_nop 1
	v_pk_mul_f32 v[42:43], v[32:33], v[130:131]
	v_pk_mul_f32 v[32:33], v[30:31], v[134:135]
	v_cvt_pk_bf16_f32 v30, v38, v39
	v_cvt_pk_bf16_f32 v31, v40, v41
	s_nop 0
	v_cvt_pk_bf16_f32 v32, v32, v33
	v_cvt_pk_bf16_f32 v33, v42, v43
	global_store_dwordx4 v[46:47], v[30:33], off offset:256 nt
	s_nop 1
	v_lshl_add_u64 v[30:31], v[132:133], 0, s[0:1]
	v_pk_mul_f32 v[32:33], v[36:37], v[158:159]
	s_mov_b32 s0, 0x500000
	v_pk_mul_f32 v[36:37], v[28:29], v[172:173]
	v_pk_mul_f32 v[28:29], v[26:27], v[170:171]
	v_cvt_pk_bf16_f32 v27, v32, v33
	v_add_co_u32_e32 v32, vcc, s0, v132
	v_cvt_pk_bf16_f32 v26, v34, v35
	v_cvt_pk_bf16_f32 v28, v28, v29
	v_cvt_pk_bf16_f32 v29, v36, v37
	s_mov_b64 s[0:1], 0x580000
	s_nop 0
	v_addc_co_u32_e32 v33, vcc, 0, v133, vcc
	global_store_dwordx4 v[32:33], v[26:29], off nt
	s_nop 1
	v_pk_mul_f32 v[26:27], v[16:17], v[130:131]
	v_pk_mul_f32 v[16:17], v[14:15], v[134:135]
	v_cvt_pk_bf16_f32 v14, v22, v23
	v_cvt_pk_bf16_f32 v15, v24, v25
	s_nop 0
	v_cvt_pk_bf16_f32 v16, v16, v17
	v_cvt_pk_bf16_f32 v17, v26, v27
	global_store_dwordx4 v[30:31], v[14:17], off offset:256 nt
	s_nop 1
	v_lshl_add_u64 v[14:15], v[132:133], 0, s[0:1]
	v_pk_mul_f32 v[16:17], v[20:21], v[158:159]
	s_mov_b32 s0, 0x580000
	v_pk_mul_f32 v[20:21], v[12:13], v[172:173]
	v_pk_mul_f32 v[12:13], v[10:11], v[170:171]
	v_cvt_pk_bf16_f32 v11, v16, v17
	v_add_co_u32_e32 v16, vcc, s0, v132
	v_cvt_pk_bf16_f32 v10, v18, v19
	v_cvt_pk_bf16_f32 v12, v12, v13
	v_cvt_pk_bf16_f32 v13, v20, v21
	s_mov_b64 s[0:1], -1
	s_nop 0
	v_addc_co_u32_e32 v17, vcc, 0, v133, vcc
	global_store_dwordx4 v[16:17], v[10:13], off nt
	s_andn2_b64 vcc, exec, s[40:41]
	s_nop 0
	v_pk_mul_f32 v[10:11], v[4:5], v[130:131]
	v_pk_mul_f32 v[4:5], v[2:3], v[134:135]
	v_cvt_pk_bf16_f32 v2, v6, v7
	v_cvt_pk_bf16_f32 v3, v8, v9
	s_nop 0
	v_cvt_pk_bf16_f32 v4, v4, v5
	v_cvt_pk_bf16_f32 v5, v10, v11
	global_store_dwordx4 v[14:15], v[2:5], off offset:256 nt
	s_cbranch_vccnz .LBB0_774
	s_andn2_b64 vcc, exec, s[26:27]
	s_cbranch_vccnz .LBB0_773
	s_barrier
	s_branch .LBB0_773
